# weight-conversion transposes: row-load loops unrolled by two, 16 loads in flight per wave with counted waits
# baseline (speedup 1.0000x reference)
; __device__ __forceinline__ unsigned cvt_pk_bf16(float lo, float hi) { unsigned r; asm volatile("v_cvt_pk_bf16_f32 %0, %1, %2" : "=v"(r) : "v"(lo), "v"(hi)); return r; }
; template <int MAP>
; __device__ __forceinline__ void transpose_item(const float* __restrict__ W, int K, int N, bf16_t* __restrict__ WT, float* scr, int item, int lane) {
;     ...
;     for (int i = 0; i < 32; ++i) { const int kk = 2 * i + (lane >> 5); scr[kk * 33 + (lane & 31)] = __builtin_nontemporal_load(W + (size_t)(k0 + kk) * N + n0 + (lane & 31)); }
;     asm volatile("s_waitcnt lgkmcnt(0)" ::: "memory");
;     const int c = lane & 7;
; #pragma unroll
;     for (int j = 0; j < 4; ++j) { const int n = (lane >> 3) + 8 * j; const float* s = scr + (8 * c) * 33 + n;
;         u32x4 o; o.x = cvt_pk_bf16(s[0 * 33], s[1 * 33]); o.y = cvt_pk_bf16(s[2 * 33], s[3 * 33]); o.z = cvt_pk_bf16(s[4 * 33], s[5 * 33]); o.w = cvt_pk_bf16(s[6 * 33], s[7 * 33]);
;         if (MAP == 1) *(u32x4*)(WT + (size_t)row_map<MAP>(n0 + n) * K + k0 + 8 * c) = o;
;         else __builtin_nontemporal_store(o, (u32x4*)(WT + (size_t)row_map<MAP>(n0 + n) * K + k0 + 8 * c)); }
; __device__ __forceinline__ void convert_weights(const Args& a, int l, unsigned char* lds, int gw, int NGW, int wave, int lane) {
;     ...
;         transpose_item<0>(w_dn, FF, DM, (bf16_t*)(ws + WS_WDN), scr, r, lane);
.LBB0_42:
	v_lshl_add_u64 v[70:71], v[44:45], 0, s[8:9]
	v_lshl_add_u64 v[72:73], v[42:43], 0, s[8:9]
	v_lshl_add_u64 v[74:75], v[40:41], 0, s[8:9]
	v_lshl_add_u64 v[76:77], v[38:39], 0, s[8:9]
	v_lshl_add_u64 v[78:79], v[36:37], 0, s[8:9]
	v_lshl_add_u64 v[80:81], v[34:35], 0, s[8:9]
	v_lshl_add_u64 v[82:83], v[2:3], 0, s[8:9]
	v_lshl_add_u64 v[84:85], v[0:1], 0, s[8:9]
	global_load_dword v69, v[70:71], off nt
	global_load_dword v86, v[72:73], off nt
	global_load_dword v87, v[74:75], off nt
	global_load_dword v88, v[76:77], off nt
	global_load_dword v89, v[78:79], off nt
	global_load_dword v90, v[80:81], off nt
	global_load_dword v91, v[82:83], off nt
	global_load_dword v92, v[84:85], off nt
	s_add_u32 s8, s8, 0x20000
	s_addc_u32 s9, s9, 0
	v_add_u32_e32 v70, 0x400, v6
	s_cmp_lg_u32 s8, 0x80000
	v_lshl_add_u64 v[130:131], v[44:45], 0, s[8:9]
	v_lshl_add_u64 v[132:133], v[42:43], 0, s[8:9]
	v_lshl_add_u64 v[134:135], v[40:41], 0, s[8:9]
	v_lshl_add_u64 v[136:137], v[38:39], 0, s[8:9]
	v_lshl_add_u64 v[138:139], v[36:37], 0, s[8:9]
	v_lshl_add_u64 v[140:141], v[34:35], 0, s[8:9]
	v_lshl_add_u64 v[142:143], v[2:3], 0, s[8:9]
	v_lshl_add_u64 v[144:145], v[0:1], 0, s[8:9]
	global_load_dword v129, v[130:131], off nt
	global_load_dword v146, v[132:133], off nt
	global_load_dword v147, v[134:135], off nt
	global_load_dword v148, v[136:137], off nt
	global_load_dword v149, v[138:139], off nt
	global_load_dword v150, v[140:141], off nt
	global_load_dword v151, v[142:143], off nt
	global_load_dword v152, v[144:145], off nt
	s_add_u32 s8, s8, 0x20000
	s_addc_u32 s9, s9, 0
	v_add_u32_e32 v130, 0xc40, v6
	s_cmp_lg_u32 s8, 0x80000
	s_waitcnt vmcnt(14)
	ds_write2_b32 v6, v69, v86 offset1:66
	s_waitcnt vmcnt(12)
	ds_write2_b32 v6, v87, v88 offset0:132 offset1:198
	s_waitcnt vmcnt(10)
	ds_write2_b32 v70, v89, v90 offset0:8 offset1:74
	s_waitcnt vmcnt(8)
	ds_write2_b32 v70, v91, v92 offset0:140 offset1:206
	v_add_u32_e32 v6, 0x840, v6
	s_waitcnt vmcnt(6)
	ds_write2_b32 v6, v129, v146 offset1:66
	s_waitcnt vmcnt(4)
	ds_write2_b32 v6, v147, v148 offset0:132 offset1:198
	s_waitcnt vmcnt(2)
	ds_write2_b32 v130, v149, v150 offset0:8 offset1:74
	s_waitcnt vmcnt(0)
	ds_write2_b32 v130, v151, v152 offset0:140 offset1:206
	v_add_u32_e32 v6, 0x840, v6
	s_cbranch_scc1 .LBB0_42
	s_add_i32 s6, s27, 0xffffa200
	s_and_b32 s8, s6, 0x1fc0
	s_lshl_b32 s6, s6, 5
	s_waitcnt lgkmcnt(0)
	s_and_b32 s9, s6, 0x7e0
	ds_read2_b32 v[0:1], v47 offset1:33
	v_or_b32_e32 v6, s9, v46
	s_waitcnt lgkmcnt(0)
	v_cvt_pk_bf16_f32 v0, v0, v1
	ds_read2_b32 v[2:3], v47 offset0:66 offset1:99
	s_lshl_b32 s6, s8, 1
	v_mul_u32_u24_e32 v6, 0x1600, v6
	s_waitcnt lgkmcnt(0)
	v_cvt_pk_bf16_f32 v1, v2, v3
	ds_read2_b32 v[2:3], v47 offset0:132 offset1:165
	v_lshl_add_u64 v[36:37], v[8:9], 0, s[6:7]
	v_lshlrev_b32_e32 v6, 1, v6
	s_waitcnt lgkmcnt(0)
	v_cvt_pk_bf16_f32 v2, v2, v3
	ds_read2_b32 v[34:35], v47 offset0:198 offset1:231
	s_waitcnt lgkmcnt(0)
	v_cvt_pk_bf16_f32 v3, v34, v35
	v_lshl_add_u64 v[38:39], v[36:37], 0, v[6:7]
	v_or_b32_e32 v6, s9, v48
	ds_read2_b32 v[34:35], v47 offset0:8 offset1:41
	global_store_dwordx4 v[38:39], v[0:3], off nt
	v_mul_u32_u24_e32 v6, 0x1600, v6
	v_lshlrev_b32_e32 v6, 1, v6
	s_waitcnt lgkmcnt(0)
	v_cvt_pk_bf16_f32 v0, v34, v35
	ds_read2_b32 v[2:3], v47 offset0:74 offset1:107
	s_waitcnt lgkmcnt(0)
	v_cvt_pk_bf16_f32 v1, v2, v3
	ds_read2_b32 v[2:3], v47 offset0:140 offset1:173
	s_waitcnt lgkmcnt(0)
	v_cvt_pk_bf16_f32 v2, v2, v3
	ds_read2_b32 v[34:35], v47 offset0:206 offset1:239
	s_waitcnt lgkmcnt(0)
	v_cvt_pk_bf16_f32 v3, v34, v35
	v_lshl_add_u64 v[38:39], v[36:37], 0, v[6:7]
	v_or_b32_e32 v6, s9, v49
	ds_read2_b32 v[34:35], v47 offset0:16 offset1:49
	global_store_dwordx4 v[38:39], v[0:3], off nt
	v_mul_u32_u24_e32 v6, 0x1600, v6
	v_lshlrev_b32_e32 v6, 1, v6
	s_waitcnt lgkmcnt(0)
	v_cvt_pk_bf16_f32 v0, v34, v35
	ds_read2_b32 v[2:3], v47 offset0:82 offset1:115
	s_waitcnt lgkmcnt(0)
	v_cvt_pk_bf16_f32 v1, v2, v3
	ds_read2_b32 v[2:3], v47 offset0:148 offset1:181
	s_waitcnt lgkmcnt(0)
	v_cvt_pk_bf16_f32 v2, v2, v3
	ds_read2_b32 v[34:35], v47 offset0:214 offset1:247
	s_waitcnt lgkmcnt(0)
	v_cvt_pk_bf16_f32 v3, v34, v35
	v_lshl_add_u64 v[38:39], v[36:37], 0, v[6:7]
	ds_read2_b32 v[34:35], v47 offset0:24 offset1:57
	global_store_dwordx4 v[38:39], v[0:3], off nt
	s_waitcnt lgkmcnt(0)
	s_nop 0
	v_cvt_pk_bf16_f32 v0, v34, v35
	ds_read2_b32 v[2:3], v47 offset0:90 offset1:123
	s_waitcnt lgkmcnt(0)
	v_cvt_pk_bf16_f32 v1, v2, v3
	ds_read2_b32 v[2:3], v47 offset0:156 offset1:189
	s_waitcnt lgkmcnt(0)
	v_cvt_pk_bf16_f32 v2, v2, v3
	v_or_b32_e32 v3, s9, v50
	v_mul_u32_u24_e32 v3, 0x1600, v3
	ds_read2_b32 v[34:35], v47 offset0:222 offset1:255
	v_lshlrev_b32_e32 v6, 1, v3
	s_waitcnt lgkmcnt(0)
	v_cvt_pk_bf16_f32 v3, v34, v35
	v_lshl_add_u64 v[34:35], v[36:37], 0, v[6:7]
	global_store_dwordx4 v[34:35], v[0:3], off nt
	s_waitcnt lgkmcnt(0)
	s_mov_b64 s[8:9], 0

; __device__ __forceinline__ unsigned cvt_pk_bf16(float lo, float hi) { unsigned r; asm volatile("v_cvt_pk_bf16_f32 %0, %1, %2" : "=v"(r) : "v"(lo), "v"(hi)); return r; }
; template <int MAP>
; __device__ __forceinline__ void transpose_item(const float* __restrict__ W, int K, int N, bf16_t* __restrict__ WT, float* scr, int item, int lane) {
;     ...
;     for (int i = 0; i < 32; ++i) { const int kk = 2 * i + (lane >> 5); scr[kk * 33 + (lane & 31)] = __builtin_nontemporal_load(W + (size_t)(k0 + kk) * N + n0 + (lane & 31)); }
;     asm volatile("s_waitcnt lgkmcnt(0)" ::: "memory");
;     const int c = lane & 7;
; #pragma unroll
;     for (int j = 0; j < 4; ++j) { const int n = (lane >> 3) + 8 * j; const float* s = scr + (8 * c) * 33 + n;
;         u32x4 o; o.x = cvt_pk_bf16(s[0 * 33], s[1 * 33]); o.y = cvt_pk_bf16(s[2 * 33], s[3 * 33]); o.z = cvt_pk_bf16(s[4 * 33], s[5 * 33]); o.w = cvt_pk_bf16(s[6 * 33], s[7 * 33]);
;         if (MAP == 1) *(u32x4*)(WT + (size_t)row_map<MAP>(n0 + n) * K + k0 + 8 * c) = o;
;         else __builtin_nontemporal_store(o, (u32x4*)(WT + (size_t)row_map<MAP>(n0 + n) * K + k0 + 8 * c)); }
; __device__ __forceinline__ void convert_weights(const Args& a, int l, unsigned char* lds, int gw, int NGW, int wave, int lane) {
;     ...
;         if (r < I_UP) { transpose_item<2>(w_up, DM, FF2, (bf16_t*)(ws + WS_WUP), scr, r, lane); continue; } r -= I_UP;
.LBB0_46:
	v_lshl_add_u64 v[42:43], v[40:41], 0, s[8:9]
	v_lshl_add_u64 v[44:45], v[38:39], 0, s[8:9]
	global_load_dword v69, v[42:43], off nt
	v_add_co_u32_e32 v42, vcc, 0x16000, v44
	v_lshl_add_u64 v[70:71], v[36:37], 0, s[8:9]
	s_nop 0
	v_addc_co_u32_e32 v43, vcc, 0, v45, vcc
	v_add_co_u32_e32 v78, vcc, 0x2c000, v44
	global_load_dword v80, v[42:43], off nt
	s_nop 0
	v_addc_co_u32_e32 v79, vcc, 0, v45, vcc
	v_add_co_u32_e32 v42, vcc, 0x42000, v44
	v_lshl_add_u64 v[72:73], v[34:35], 0, s[8:9]
	v_lshl_add_u64 v[74:75], v[2:3], 0, s[8:9]
	v_lshl_add_u64 v[76:77], v[0:1], 0, s[8:9]
	v_addc_co_u32_e32 v43, vcc, 0, v45, vcc
	global_load_dword v44, v[78:79], off nt
	global_load_dword v45, v[42:43], off nt
	global_load_dword v81, v[70:71], off nt
	global_load_dword v82, v[72:73], off nt
	global_load_dword v83, v[74:75], off nt
	global_load_dword v84, v[76:77], off nt
	s_add_u32 s8, s8, 0xb0000
	s_addc_u32 s9, s9, 0
	v_add_u32_e32 v42, 0x400, v6
	s_cmp_lg_u32 s8, 0x2c0000
	v_lshl_add_u64 v[102:103], v[40:41], 0, s[8:9]
	v_lshl_add_u64 v[104:105], v[38:39], 0, s[8:9]
	global_load_dword v129, v[102:103], off nt
	v_add_co_u32_e32 v102, vcc, 0x16000, v104
	v_lshl_add_u64 v[130:131], v[36:37], 0, s[8:9]
	s_nop 0
	v_addc_co_u32_e32 v103, vcc, 0, v105, vcc
	v_add_co_u32_e32 v138, vcc, 0x2c000, v104
	global_load_dword v140, v[102:103], off nt
	s_nop 0
	v_addc_co_u32_e32 v139, vcc, 0, v105, vcc
	v_add_co_u32_e32 v102, vcc, 0x42000, v104
	v_lshl_add_u64 v[132:133], v[34:35], 0, s[8:9]
	v_lshl_add_u64 v[134:135], v[2:3], 0, s[8:9]
	v_lshl_add_u64 v[136:137], v[0:1], 0, s[8:9]
	v_addc_co_u32_e32 v103, vcc, 0, v105, vcc
	global_load_dword v104, v[138:139], off nt
	global_load_dword v105, v[102:103], off nt
	global_load_dword v141, v[130:131], off nt
	global_load_dword v142, v[132:133], off nt
	global_load_dword v143, v[134:135], off nt
	global_load_dword v144, v[136:137], off nt
	s_add_u32 s8, s8, 0xb0000
	s_addc_u32 s9, s9, 0
	v_add_u32_e32 v102, 0xc40, v6
	s_cmp_lg_u32 s8, 0x2c0000
	s_waitcnt vmcnt(14)
	ds_write2_b32 v6, v69, v80 offset1:66
	s_waitcnt vmcnt(12)
	ds_write2_b32 v6, v44, v45 offset0:132 offset1:198
	s_waitcnt vmcnt(10)
	ds_write2_b32 v42, v81, v82 offset0:8 offset1:74
	s_waitcnt vmcnt(8)
	ds_write2_b32 v42, v83, v84 offset0:140 offset1:206
	v_add_u32_e32 v6, 0x840, v6
	s_waitcnt vmcnt(6)
	ds_write2_b32 v6, v129, v140 offset1:66
	s_waitcnt vmcnt(4)
	ds_write2_b32 v6, v104, v105 offset0:132 offset1:198
	s_waitcnt vmcnt(2)
	ds_write2_b32 v102, v141, v142 offset0:8 offset1:74
	s_waitcnt vmcnt(0)
	ds_write2_b32 v102, v143, v144 offset0:140 offset1:206
	v_add_u32_e32 v6, 0x840, v6
	s_cbranch_scc1 .LBB0_46
	s_waitcnt lgkmcnt(0)
	s_and_b32 s6, 0xffff, s11
	ds_read2_b32 v[0:1], v47 offset1:33
	s_and_b32 s12, 0xffff, s12
	s_and_b32 s8, 0xffff, s10
	s_lshl_b32 s6, s6, 1
	s_waitcnt lgkmcnt(0)
	v_cvt_pk_bf16_f32 v0, v0, v1
	ds_read2_b32 v[2:3], v47 offset0:66 offset1:99
	v_or_b32_e32 v6, s12, v46
	s_cmpk_lt_u32 s8, 0xb0
	s_waitcnt lgkmcnt(0)
	v_cvt_pk_bf16_f32 v1, v2, v3
	ds_read2_b32 v[2:3], v47 offset0:132 offset1:165
	v_add_u32_e32 v38, 0xffffea00, v6
	s_cselect_b64 vcc, -1, 0
	s_waitcnt lgkmcnt(0)
	v_cvt_pk_bf16_f32 v2, v2, v3
	v_cndmask_b32_e32 v3, v38, v6, vcc
	v_lshlrev_b32_e32 v6, 1, v3
	s_and_b64 s[8:9], vcc, exec
	v_lshl_add_u64 v[34:35], v[10:11], 0, s[6:7]
	ds_read2_b32 v[36:37], v47 offset0:198 offset1:231
	v_and_b32_e32 v38, 0x67, v3
	v_and_b32_e32 v6, 0xffffff00, v6
	s_cselect_b32 s6, 0, 0x80
	s_waitcnt lgkmcnt(0)
	v_cvt_pk_bf16_f32 v3, v36, v37
	v_or3_b32 v36, v38, v6, s6
	v_ashrrev_i32_e32 v37, 31, v36
	v_lshlrev_b64 v[36:37], 12, v[36:37]
	v_lshl_add_u64 v[36:37], v[34:35], 0, v[36:37]
	ds_read2_b32 v[38:39], v47 offset0:8 offset1:41
	global_store_dwordx4 v[36:37], v[0:3], off nt
	v_or_b32_e32 v6, s12, v48
	s_waitcnt lgkmcnt(0)
	v_cvt_pk_bf16_f32 v0, v38, v39
	ds_read2_b32 v[2:3], v47 offset0:74 offset1:107
	s_waitcnt lgkmcnt(0)
	v_cvt_pk_bf16_f32 v1, v2, v3
	ds_read2_b32 v[2:3], v47 offset0:140 offset1:173
	s_waitcnt lgkmcnt(0)
	v_cvt_pk_bf16_f32 v2, v2, v3
	v_add_u32_e32 v3, 0xffffea00, v6
	v_cndmask_b32_e32 v6, v3, v6, vcc
	v_lshlrev_b32_e32 v3, 1, v6
	ds_read2_b32 v[36:37], v47 offset0:206 offset1:239
	v_and_b32_e32 v38, 0xffffff00, v3
	v_and_b32_e32 v6, 0x6f, v6
	s_waitcnt lgkmcnt(0)
	v_cvt_pk_bf16_f32 v3, v36, v37
	v_or3_b32 v36, v6, v38, s6
	v_ashrrev_i32_e32 v37, 31, v36
	v_lshlrev_b64 v[36:37], 12, v[36:37]
	v_lshl_add_u64 v[36:37], v[34:35], 0, v[36:37]
	ds_read2_b32 v[38:39], v47 offset0:16 offset1:49
	global_store_dwordx4 v[36:37], v[0:3], off nt
	v_or_b32_e32 v6, s12, v49
	s_waitcnt lgkmcnt(0)
	v_cvt_pk_bf16_f32 v0, v38, v39
	ds_read2_b32 v[2:3], v47 offset0:82 offset1:115
	s_waitcnt lgkmcnt(0)
	v_cvt_pk_bf16_f32 v1, v2, v3
	ds_read2_b32 v[2:3], v47 offset0:148 offset1:181
	v_add_u32_e32 v38, 0xffffea00, v6
	s_waitcnt lgkmcnt(0)
	v_cvt_pk_bf16_f32 v2, v2, v3
	v_cndmask_b32_e32 v3, v38, v6, vcc
	v_lshlrev_b32_e32 v6, 1, v3
	ds_read2_b32 v[36:37], v47 offset0:214 offset1:247
	v_and_b32_e32 v38, 0x77, v3
	v_and_b32_e32 v6, 0xffffff00, v6
	s_waitcnt lgkmcnt(0)
	v_cvt_pk_bf16_f32 v3, v36, v37
	v_or3_b32 v36, v38, v6, s6
	v_ashrrev_i32_e32 v37, 31, v36
	v_lshlrev_b64 v[36:37], 12, v[36:37]
	v_lshl_add_u64 v[36:37], v[34:35], 0, v[36:37]
	v_or_b32_e32 v6, s12, v50
	ds_read2_b32 v[38:39], v47 offset0:24 offset1:57
	global_store_dwordx4 v[36:37], v[0:3], off nt
	v_add_u32_e32 v36, 0xffffea00, v6
	v_cndmask_b32_e32 v6, v36, v6, vcc
	s_waitcnt lgkmcnt(0)
	v_cvt_pk_bf16_f32 v0, v38, v39
	ds_read2_b32 v[2:3], v47 offset0:90 offset1:123
	s_waitcnt lgkmcnt(0)
	v_cvt_pk_bf16_f32 v1, v2, v3
	ds_read2_b32 v[2:3], v47 offset0:156 offset1:189
	s_waitcnt lgkmcnt(0)
	v_cvt_pk_bf16_f32 v2, v2, v3
	v_lshlrev_b32_e32 v3, 1, v6
	v_and_b32_e32 v6, 0x7f, v6
	v_and_b32_e32 v3, 0xffffff00, v3
	v_or3_b32 v38, v6, v3, s6
	ds_read2_b32 v[36:37], v47 offset0:222 offset1:255
	v_ashrrev_i32_e32 v39, 31, v38
	s_waitcnt lgkmcnt(0)
	v_cvt_pk_bf16_f32 v3, v36, v37
	v_lshlrev_b64 v[36:37], 12, v[38:39]
	v_lshl_add_u64 v[34:35], v[34:35], 0, v[36:37]
	global_store_dwordx4 v[34:35], v[0:3], off nt
	s_waitcnt lgkmcnt(0)

; __device__ __forceinline__ unsigned cvt_pk_bf16(float lo, float hi) { unsigned r; asm volatile("v_cvt_pk_bf16_f32 %0, %1, %2" : "=v"(r) : "v"(lo), "v"(hi)); return r; }
; template <int MAP>
; __device__ __forceinline__ void transpose_item(const float* __restrict__ W, int K, int N, bf16_t* __restrict__ WT, float* scr, int item, int lane) {
;     ...
;     for (int i = 0; i < 32; ++i) { const int kk = 2 * i + (lane >> 5); scr[kk * 33 + (lane & 31)] = __builtin_nontemporal_load(W + (size_t)(k0 + kk) * N + n0 + (lane & 31)); }
;     asm volatile("s_waitcnt lgkmcnt(0)" ::: "memory");
;     const int c = lane & 7;
; #pragma unroll
;     for (int j = 0; j < 4; ++j) { const int n = (lane >> 3) + 8 * j; const float* s = scr + (8 * c) * 33 + n;
;         u32x4 o; o.x = cvt_pk_bf16(s[0 * 33], s[1 * 33]); o.y = cvt_pk_bf16(s[2 * 33], s[3 * 33]); o.z = cvt_pk_bf16(s[4 * 33], s[5 * 33]); o.w = cvt_pk_bf16(s[6 * 33], s[7 * 33]);
;         if (MAP == 1) *(u32x4*)(WT + (size_t)row_map<MAP>(n0 + n) * K + k0 + 8 * c) = o;
;         else __builtin_nontemporal_store(o, (u32x4*)(WT + (size_t)row_map<MAP>(n0 + n) * K + k0 + 8 * c)); }
; __device__ __forceinline__ void convert_weights(const Args& a, int l, unsigned char* lds, int gw, int NGW, int wave, int lane) {
;     ...
;         if (r < I_O) { transpose_item<0>(w_o, DM, DM, (bf16_t*)(ws + WS_WO), scr, r, lane); continue; } r -= I_O;
.LBB0_51:
	v_lshl_add_u64 v[70:71], v[44:45], 0, s[8:9]
	v_lshl_add_u64 v[72:73], v[42:43], 0, s[8:9]
	v_lshl_add_u64 v[74:75], v[40:41], 0, s[8:9]
	v_lshl_add_u64 v[76:77], v[38:39], 0, s[8:9]
	v_lshl_add_u64 v[78:79], v[36:37], 0, s[8:9]
	v_lshl_add_u64 v[80:81], v[34:35], 0, s[8:9]
	v_lshl_add_u64 v[82:83], v[2:3], 0, s[8:9]
	v_lshl_add_u64 v[84:85], v[0:1], 0, s[8:9]
	global_load_dword v69, v[70:71], off nt
	global_load_dword v86, v[72:73], off nt
	global_load_dword v87, v[74:75], off nt
	global_load_dword v88, v[76:77], off nt
	global_load_dword v89, v[78:79], off nt
	global_load_dword v90, v[80:81], off nt
	global_load_dword v91, v[82:83], off nt
	global_load_dword v92, v[84:85], off nt
	s_add_u32 s8, s8, 0x20000
	s_addc_u32 s9, s9, 0
	v_add_u32_e32 v70, 0x400, v6
	s_cmp_lg_u32 s8, 0x80000
	v_lshl_add_u64 v[130:131], v[44:45], 0, s[8:9]
	v_lshl_add_u64 v[132:133], v[42:43], 0, s[8:9]
	v_lshl_add_u64 v[134:135], v[40:41], 0, s[8:9]
	v_lshl_add_u64 v[136:137], v[38:39], 0, s[8:9]
	v_lshl_add_u64 v[138:139], v[36:37], 0, s[8:9]
	v_lshl_add_u64 v[140:141], v[34:35], 0, s[8:9]
	v_lshl_add_u64 v[142:143], v[2:3], 0, s[8:9]
	v_lshl_add_u64 v[144:145], v[0:1], 0, s[8:9]
	global_load_dword v129, v[130:131], off nt
	global_load_dword v146, v[132:133], off nt
	global_load_dword v147, v[134:135], off nt
	global_load_dword v148, v[136:137], off nt
	global_load_dword v149, v[138:139], off nt
	global_load_dword v150, v[140:141], off nt
	global_load_dword v151, v[142:143], off nt
	global_load_dword v152, v[144:145], off nt
	s_add_u32 s8, s8, 0x20000
	s_addc_u32 s9, s9, 0
	v_add_u32_e32 v130, 0xc40, v6
	s_cmp_lg_u32 s8, 0x80000
	s_waitcnt vmcnt(14)
	ds_write2_b32 v6, v69, v86 offset1:66
	s_waitcnt vmcnt(12)
	ds_write2_b32 v6, v87, v88 offset0:132 offset1:198
	s_waitcnt vmcnt(10)
	ds_write2_b32 v70, v89, v90 offset0:8 offset1:74
	s_waitcnt vmcnt(8)
	ds_write2_b32 v70, v91, v92 offset0:140 offset1:206
	v_add_u32_e32 v6, 0x840, v6
	s_waitcnt vmcnt(6)
	ds_write2_b32 v6, v129, v146 offset1:66
	s_waitcnt vmcnt(4)
	ds_write2_b32 v6, v147, v148 offset0:132 offset1:198
	s_waitcnt vmcnt(2)
	ds_write2_b32 v130, v149, v150 offset0:8 offset1:74
	s_waitcnt vmcnt(0)
	ds_write2_b32 v130, v151, v152 offset0:140 offset1:206
	v_add_u32_e32 v6, 0x840, v6
	s_cbranch_scc1 .LBB0_51
	s_add_i32 s6, s27, 0xffffd600
	s_waitcnt lgkmcnt(0)
	s_and_b32 s8, s6, 0x1fc0
	s_lshl_b32 s6, s6, 5
	ds_read2_b32 v[0:1], v47 offset1:33
	s_and_b32 s9, s6, 0x7e0
	s_waitcnt lgkmcnt(0)
	v_cvt_pk_bf16_f32 v0, v0, v1
	ds_read2_b32 v[2:3], v47 offset0:66 offset1:99
	s_lshl_b32 s6, s8, 1
	v_or_b32_e32 v6, s9, v46
	s_waitcnt lgkmcnt(0)
	v_cvt_pk_bf16_f32 v1, v2, v3
	ds_read2_b32 v[2:3], v47 offset0:132 offset1:165
	v_lshl_add_u64 v[36:37], v[12:13], 0, s[6:7]
	v_lshlrev_b32_e32 v6, 12, v6
	s_waitcnt lgkmcnt(0)
	v_cvt_pk_bf16_f32 v2, v2, v3
	ds_read2_b32 v[34:35], v47 offset0:198 offset1:231
	s_waitcnt lgkmcnt(0)
	v_cvt_pk_bf16_f32 v3, v34, v35
	v_lshl_add_u64 v[38:39], v[36:37], 0, v[6:7]
	ds_read2_b32 v[34:35], v47 offset0:8 offset1:41
	global_store_dwordx4 v[38:39], v[0:3], off nt
	v_or_b32_e32 v6, s9, v48
	v_lshlrev_b32_e32 v6, 12, v6
	s_waitcnt lgkmcnt(0)
	v_cvt_pk_bf16_f32 v0, v34, v35
	ds_read2_b32 v[2:3], v47 offset0:74 offset1:107
	s_waitcnt lgkmcnt(0)
	v_cvt_pk_bf16_f32 v1, v2, v3
	ds_read2_b32 v[2:3], v47 offset0:140 offset1:173
	s_waitcnt lgkmcnt(0)
	v_cvt_pk_bf16_f32 v2, v2, v3
	ds_read2_b32 v[34:35], v47 offset0:206 offset1:239
	s_waitcnt lgkmcnt(0)
	v_cvt_pk_bf16_f32 v3, v34, v35
	v_lshl_add_u64 v[38:39], v[36:37], 0, v[6:7]
	ds_read2_b32 v[34:35], v47 offset0:16 offset1:49
	global_store_dwordx4 v[38:39], v[0:3], off nt
	v_or_b32_e32 v6, s9, v49
	v_lshlrev_b32_e32 v6, 12, v6
	s_waitcnt lgkmcnt(0)
	v_cvt_pk_bf16_f32 v0, v34, v35
	ds_read2_b32 v[2:3], v47 offset0:82 offset1:115
	s_waitcnt lgkmcnt(0)
	v_cvt_pk_bf16_f32 v1, v2, v3
	ds_read2_b32 v[2:3], v47 offset0:148 offset1:181
	s_waitcnt lgkmcnt(0)
	v_cvt_pk_bf16_f32 v2, v2, v3
	ds_read2_b32 v[34:35], v47 offset0:214 offset1:247
	s_waitcnt lgkmcnt(0)
	v_cvt_pk_bf16_f32 v3, v34, v35
	v_lshl_add_u64 v[38:39], v[36:37], 0, v[6:7]
	ds_read2_b32 v[34:35], v47 offset0:24 offset1:57
	global_store_dwordx4 v[38:39], v[0:3], off nt
	s_waitcnt lgkmcnt(0)
	s_nop 0
	v_cvt_pk_bf16_f32 v0, v34, v35
	ds_read2_b32 v[2:3], v47 offset0:90 offset1:123
	s_waitcnt lgkmcnt(0)
	v_cvt_pk_bf16_f32 v1, v2, v3
	ds_read2_b32 v[2:3], v47 offset0:156 offset1:189
	s_waitcnt lgkmcnt(0)
	v_cvt_pk_bf16_f32 v2, v2, v3
	v_or_b32_e32 v3, s9, v50
	ds_read2_b32 v[34:35], v47 offset0:222 offset1:255
	v_lshlrev_b32_e32 v6, 12, v3
	s_waitcnt lgkmcnt(0)
	v_cvt_pk_bf16_f32 v3, v34, v35
	v_lshl_add_u64 v[34:35], v[36:37], 0, v[6:7]
	global_store_dwordx4 v[34:35], v[0:3], off nt
	s_waitcnt lgkmcnt(0)

; __device__ __forceinline__ unsigned cvt_pk_bf16(float lo, float hi) { unsigned r; asm volatile("v_cvt_pk_bf16_f32 %0, %1, %2" : "=v"(r) : "v"(lo), "v"(hi)); return r; }
; template <int MAP>
; __device__ __forceinline__ void transpose_item(const float* __restrict__ W, int K, int N, bf16_t* __restrict__ WT, float* scr, int item, int lane) {
;     ...
;     for (int i = 0; i < 32; ++i) { const int kk = 2 * i + (lane >> 5); scr[kk * 33 + (lane & 31)] = __builtin_nontemporal_load(W + (size_t)(k0 + kk) * N + n0 + (lane & 31)); }
;     asm volatile("s_waitcnt lgkmcnt(0)" ::: "memory");
;     const int c = lane & 7;
; #pragma unroll
;     for (int j = 0; j < 4; ++j) { const int n = (lane >> 3) + 8 * j; const float* s = scr + (8 * c) * 33 + n;
;         u32x4 o; o.x = cvt_pk_bf16(s[0 * 33], s[1 * 33]); o.y = cvt_pk_bf16(s[2 * 33], s[3 * 33]); o.z = cvt_pk_bf16(s[4 * 33], s[5 * 33]); o.w = cvt_pk_bf16(s[6 * 33], s[7 * 33]);
;         if (MAP == 1) *(u32x4*)(WT + (size_t)row_map<MAP>(n0 + n) * K + k0 + 8 * c) = o;
;         else __builtin_nontemporal_store(o, (u32x4*)(WT + (size_t)row_map<MAP>(n0 + n) * K + k0 + 8 * c)); }
; __device__ __forceinline__ void convert_weights(const Args& a, int l, unsigned char* lds, int gw, int NGW, int wave, int lane) {
;     ...
;         if (r < I_PA) { transpose_item<0>(w_pb, 1024, DM, (bf16_t*)(ws + WS_WPB), scr, r, lane); continue; } r -= I_PA;
.LBB0_56:
	v_lshl_add_u64 v[70:71], v[44:45], 0, s[8:9]
	v_lshl_add_u64 v[72:73], v[42:43], 0, s[8:9]
	v_lshl_add_u64 v[74:75], v[40:41], 0, s[8:9]
	v_lshl_add_u64 v[76:77], v[38:39], 0, s[8:9]
	v_lshl_add_u64 v[78:79], v[36:37], 0, s[8:9]
	v_lshl_add_u64 v[80:81], v[34:35], 0, s[8:9]
	v_lshl_add_u64 v[82:83], v[2:3], 0, s[8:9]
	v_lshl_add_u64 v[84:85], v[0:1], 0, s[8:9]
	global_load_dword v69, v[70:71], off nt
	global_load_dword v86, v[72:73], off nt
	global_load_dword v87, v[74:75], off nt
	global_load_dword v88, v[76:77], off nt
	global_load_dword v89, v[78:79], off nt
	global_load_dword v90, v[80:81], off nt
	global_load_dword v91, v[82:83], off nt
	global_load_dword v92, v[84:85], off nt
	s_add_u32 s8, s8, 0x20000
	s_addc_u32 s9, s9, 0
	v_add_u32_e32 v70, 0x400, v6
	s_cmp_lg_u32 s8, 0x80000
	v_lshl_add_u64 v[130:131], v[44:45], 0, s[8:9]
	v_lshl_add_u64 v[132:133], v[42:43], 0, s[8:9]
	v_lshl_add_u64 v[134:135], v[40:41], 0, s[8:9]
	v_lshl_add_u64 v[136:137], v[38:39], 0, s[8:9]
	v_lshl_add_u64 v[138:139], v[36:37], 0, s[8:9]
	v_lshl_add_u64 v[140:141], v[34:35], 0, s[8:9]
	v_lshl_add_u64 v[142:143], v[2:3], 0, s[8:9]
	v_lshl_add_u64 v[144:145], v[0:1], 0, s[8:9]
	global_load_dword v129, v[130:131], off nt
	global_load_dword v146, v[132:133], off nt
	global_load_dword v147, v[134:135], off nt
	global_load_dword v148, v[136:137], off nt
	global_load_dword v149, v[138:139], off nt
	global_load_dword v150, v[140:141], off nt
	global_load_dword v151, v[142:143], off nt
	global_load_dword v152, v[144:145], off nt
	s_add_u32 s8, s8, 0x20000
	s_addc_u32 s9, s9, 0
	v_add_u32_e32 v130, 0xc40, v6
	s_cmp_lg_u32 s8, 0x80000
	s_waitcnt vmcnt(14)
	ds_write2_b32 v6, v69, v86 offset1:66
	s_waitcnt vmcnt(12)
	ds_write2_b32 v6, v87, v88 offset0:132 offset1:198
	s_waitcnt vmcnt(10)
	ds_write2_b32 v70, v89, v90 offset0:8 offset1:74
	s_waitcnt vmcnt(8)
	ds_write2_b32 v70, v91, v92 offset0:140 offset1:206
	v_add_u32_e32 v6, 0x840, v6
	s_waitcnt vmcnt(6)
	ds_write2_b32 v6, v129, v146 offset1:66
	s_waitcnt vmcnt(4)
	ds_write2_b32 v6, v147, v148 offset0:132 offset1:198
	s_waitcnt vmcnt(2)
	ds_write2_b32 v130, v149, v150 offset0:8 offset1:74
	s_waitcnt vmcnt(0)
	ds_write2_b32 v130, v151, v152 offset0:140 offset1:206
	v_add_u32_e32 v6, 0x840, v6
	s_cbranch_scc1 .LBB0_56
	s_add_i32 s6, s27, 0xffffda00
	s_waitcnt lgkmcnt(0)
	s_and_b32 s8, s6, 0x1fc0
	s_lshl_b32 s6, s6, 5
	ds_read2_b32 v[0:1], v47 offset1:33
	s_and_b32 s9, s6, 0x7e0
	s_waitcnt lgkmcnt(0)
	v_cvt_pk_bf16_f32 v0, v0, v1
	ds_read2_b32 v[2:3], v47 offset0:66 offset1:99
	s_lshl_b32 s6, s8, 1
	v_or_b32_e32 v6, s9, v46
	s_waitcnt lgkmcnt(0)
	v_cvt_pk_bf16_f32 v1, v2, v3
	ds_read2_b32 v[2:3], v47 offset0:132 offset1:165
	v_lshl_add_u64 v[36:37], v[14:15], 0, s[6:7]
	v_lshlrev_b32_e32 v6, 11, v6
	s_waitcnt lgkmcnt(0)
	v_cvt_pk_bf16_f32 v2, v2, v3
	ds_read2_b32 v[34:35], v47 offset0:198 offset1:231
	s_waitcnt lgkmcnt(0)
	v_cvt_pk_bf16_f32 v3, v34, v35
	v_lshl_add_u64 v[38:39], v[36:37], 0, v[6:7]
	ds_read2_b32 v[34:35], v47 offset0:8 offset1:41
	global_store_dwordx4 v[38:39], v[0:3], off nt
	v_or_b32_e32 v6, s9, v48
	v_lshlrev_b32_e32 v6, 11, v6
	s_waitcnt lgkmcnt(0)
	v_cvt_pk_bf16_f32 v0, v34, v35
	ds_read2_b32 v[2:3], v47 offset0:74 offset1:107
	s_waitcnt lgkmcnt(0)
	v_cvt_pk_bf16_f32 v1, v2, v3
	ds_read2_b32 v[2:3], v47 offset0:140 offset1:173
	s_waitcnt lgkmcnt(0)
	v_cvt_pk_bf16_f32 v2, v2, v3
	ds_read2_b32 v[34:35], v47 offset0:206 offset1:239
	s_waitcnt lgkmcnt(0)
	v_cvt_pk_bf16_f32 v3, v34, v35
	v_lshl_add_u64 v[38:39], v[36:37], 0, v[6:7]
	ds_read2_b32 v[34:35], v47 offset0:16 offset1:49
	global_store_dwordx4 v[38:39], v[0:3], off nt
	v_or_b32_e32 v6, s9, v49
	v_lshlrev_b32_e32 v6, 11, v6
	s_waitcnt lgkmcnt(0)
	v_cvt_pk_bf16_f32 v0, v34, v35
	ds_read2_b32 v[2:3], v47 offset0:82 offset1:115
	s_waitcnt lgkmcnt(0)
	v_cvt_pk_bf16_f32 v1, v2, v3
	ds_read2_b32 v[2:3], v47 offset0:148 offset1:181
	s_waitcnt lgkmcnt(0)
	v_cvt_pk_bf16_f32 v2, v2, v3
	ds_read2_b32 v[34:35], v47 offset0:214 offset1:247
	s_waitcnt lgkmcnt(0)
	v_cvt_pk_bf16_f32 v3, v34, v35
	v_lshl_add_u64 v[38:39], v[36:37], 0, v[6:7]
	ds_read2_b32 v[34:35], v47 offset0:24 offset1:57
	global_store_dwordx4 v[38:39], v[0:3], off nt
	s_waitcnt lgkmcnt(0)
	s_nop 0
	v_cvt_pk_bf16_f32 v0, v34, v35
	ds_read2_b32 v[2:3], v47 offset0:90 offset1:123
	s_waitcnt lgkmcnt(0)
	v_cvt_pk_bf16_f32 v1, v2, v3
	ds_read2_b32 v[2:3], v47 offset0:156 offset1:189
	s_waitcnt lgkmcnt(0)
	v_cvt_pk_bf16_f32 v2, v2, v3
	v_or_b32_e32 v3, s9, v50
	ds_read2_b32 v[34:35], v47 offset0:222 offset1:255
	v_lshlrev_b32_e32 v6, 11, v3
	s_waitcnt lgkmcnt(0)
	v_cvt_pk_bf16_f32 v3, v34, v35
	v_lshl_add_u64 v[34:35], v[36:37], 0, v[6:7]
	global_store_dwordx4 v[34:35], v[0:3], off nt
	s_waitcnt lgkmcnt(0)

; __device__ __forceinline__ unsigned cvt_pk_bf16(float lo, float hi) { unsigned r; asm volatile("v_cvt_pk_bf16_f32 %0, %1, %2" : "=v"(r) : "v"(lo), "v"(hi)); return r; }
; template <int MAP>
; __device__ __forceinline__ void transpose_item(const float* __restrict__ W, int K, int N, bf16_t* __restrict__ WT, float* scr, int item, int lane) {
;     ...
;     for (int i = 0; i < 32; ++i) { const int kk = 2 * i + (lane >> 5); scr[kk * 33 + (lane & 31)] = __builtin_nontemporal_load(W + (size_t)(k0 + kk) * N + n0 + (lane & 31)); }
;     asm volatile("s_waitcnt lgkmcnt(0)" ::: "memory");
;     const int c = lane & 7;
; #pragma unroll
;     for (int j = 0; j < 4; ++j) { const int n = (lane >> 3) + 8 * j; const float* s = scr + (8 * c) * 33 + n;
;         u32x4 o; o.x = cvt_pk_bf16(s[0 * 33], s[1 * 33]); o.y = cvt_pk_bf16(s[2 * 33], s[3 * 33]); o.z = cvt_pk_bf16(s[4 * 33], s[5 * 33]); o.w = cvt_pk_bf16(s[6 * 33], s[7 * 33]);
;         if (MAP == 1) *(u32x4*)(WT + (size_t)row_map<MAP>(n0 + n) * K + k0 + 8 * c) = o;
;         else __builtin_nontemporal_store(o, (u32x4*)(WT + (size_t)row_map<MAP>(n0 + n) * K + k0 + 8 * c)); }
; __device__ __forceinline__ void convert_weights(const Args& a, int l, unsigned char* lds, int gw, int NGW, int wave, int lane) {
;     ...
;         if (r < I_PA) { transpose_item<0>(w_pa, 1024, DM, (bf16_t*)(ws + WS_WPA), scr, r, lane); continue; } r -= I_PA;
.LBB0_61:
	v_lshl_add_u64 v[70:71], v[44:45], 0, s[8:9]
	v_lshl_add_u64 v[72:73], v[42:43], 0, s[8:9]
	v_lshl_add_u64 v[74:75], v[40:41], 0, s[8:9]
	v_lshl_add_u64 v[76:77], v[38:39], 0, s[8:9]
	v_lshl_add_u64 v[78:79], v[36:37], 0, s[8:9]
	v_lshl_add_u64 v[80:81], v[34:35], 0, s[8:9]
	v_lshl_add_u64 v[82:83], v[2:3], 0, s[8:9]
	v_lshl_add_u64 v[84:85], v[0:1], 0, s[8:9]
	global_load_dword v69, v[70:71], off nt
	global_load_dword v86, v[72:73], off nt
	global_load_dword v87, v[74:75], off nt
	global_load_dword v88, v[76:77], off nt
	global_load_dword v89, v[78:79], off nt
	global_load_dword v90, v[80:81], off nt
	global_load_dword v91, v[82:83], off nt
	global_load_dword v92, v[84:85], off nt
	s_add_u32 s8, s8, 0x20000
	s_addc_u32 s9, s9, 0
	v_add_u32_e32 v70, 0x400, v6
	s_cmp_lg_u32 s8, 0x80000
	v_lshl_add_u64 v[130:131], v[44:45], 0, s[8:9]
	v_lshl_add_u64 v[132:133], v[42:43], 0, s[8:9]
	v_lshl_add_u64 v[134:135], v[40:41], 0, s[8:9]
	v_lshl_add_u64 v[136:137], v[38:39], 0, s[8:9]
	v_lshl_add_u64 v[138:139], v[36:37], 0, s[8:9]
	v_lshl_add_u64 v[140:141], v[34:35], 0, s[8:9]
	v_lshl_add_u64 v[142:143], v[2:3], 0, s[8:9]
	v_lshl_add_u64 v[144:145], v[0:1], 0, s[8:9]
	global_load_dword v129, v[130:131], off nt
	global_load_dword v146, v[132:133], off nt
	global_load_dword v147, v[134:135], off nt
	global_load_dword v148, v[136:137], off nt
	global_load_dword v149, v[138:139], off nt
	global_load_dword v150, v[140:141], off nt
	global_load_dword v151, v[142:143], off nt
	global_load_dword v152, v[144:145], off nt
	s_add_u32 s8, s8, 0x20000
	s_addc_u32 s9, s9, 0
	v_add_u32_e32 v130, 0xc40, v6
	s_cmp_lg_u32 s8, 0x80000
	s_waitcnt vmcnt(14)
	ds_write2_b32 v6, v69, v86 offset1:66
	s_waitcnt vmcnt(12)
	ds_write2_b32 v6, v87, v88 offset0:132 offset1:198
	s_waitcnt vmcnt(10)
	ds_write2_b32 v70, v89, v90 offset0:8 offset1:74
	s_waitcnt vmcnt(8)
	ds_write2_b32 v70, v91, v92 offset0:140 offset1:206
	v_add_u32_e32 v6, 0x840, v6
	s_waitcnt vmcnt(6)
	ds_write2_b32 v6, v129, v146 offset1:66
	s_waitcnt vmcnt(4)
	ds_write2_b32 v6, v147, v148 offset0:132 offset1:198
	s_waitcnt vmcnt(2)
	ds_write2_b32 v130, v149, v150 offset0:8 offset1:74
	s_waitcnt vmcnt(0)
	ds_write2_b32 v130, v151, v152 offset0:140 offset1:206
	v_add_u32_e32 v6, 0x840, v6
	s_cbranch_scc1 .LBB0_61
	s_add_i32 s6, s27, 0xffffde00
	s_waitcnt lgkmcnt(0)
	s_and_b32 s8, s6, 0x1fc0
	s_lshl_b32 s6, s6, 5
	ds_read2_b32 v[0:1], v47 offset1:33
	s_and_b32 s9, s6, 0x7e0
	s_waitcnt lgkmcnt(0)
	v_cvt_pk_bf16_f32 v0, v0, v1
	ds_read2_b32 v[2:3], v47 offset0:66 offset1:99
	s_lshl_b32 s6, s8, 1
	v_or_b32_e32 v6, s9, v46
	s_waitcnt lgkmcnt(0)
	v_cvt_pk_bf16_f32 v1, v2, v3
	ds_read2_b32 v[2:3], v47 offset0:132 offset1:165
	v_lshl_add_u64 v[36:37], v[16:17], 0, s[6:7]
	v_lshlrev_b32_e32 v6, 11, v6
	s_waitcnt lgkmcnt(0)
	v_cvt_pk_bf16_f32 v2, v2, v3
	ds_read2_b32 v[34:35], v47 offset0:198 offset1:231
	s_waitcnt lgkmcnt(0)
	v_cvt_pk_bf16_f32 v3, v34, v35
	v_lshl_add_u64 v[38:39], v[36:37], 0, v[6:7]
	ds_read2_b32 v[34:35], v47 offset0:8 offset1:41
	global_store_dwordx4 v[38:39], v[0:3], off nt
	v_or_b32_e32 v6, s9, v48
	v_lshlrev_b32_e32 v6, 11, v6
	s_waitcnt lgkmcnt(0)
	v_cvt_pk_bf16_f32 v0, v34, v35
	ds_read2_b32 v[2:3], v47 offset0:74 offset1:107
	s_waitcnt lgkmcnt(0)
	v_cvt_pk_bf16_f32 v1, v2, v3
	ds_read2_b32 v[2:3], v47 offset0:140 offset1:173
	s_waitcnt lgkmcnt(0)
	v_cvt_pk_bf16_f32 v2, v2, v3
	ds_read2_b32 v[34:35], v47 offset0:206 offset1:239
	s_waitcnt lgkmcnt(0)
	v_cvt_pk_bf16_f32 v3, v34, v35
	v_lshl_add_u64 v[38:39], v[36:37], 0, v[6:7]
	ds_read2_b32 v[34:35], v47 offset0:16 offset1:49
	global_store_dwordx4 v[38:39], v[0:3], off nt
	v_or_b32_e32 v6, s9, v49
	v_lshlrev_b32_e32 v6, 11, v6
	s_waitcnt lgkmcnt(0)
	v_cvt_pk_bf16_f32 v0, v34, v35
	ds_read2_b32 v[2:3], v47 offset0:82 offset1:115
	s_waitcnt lgkmcnt(0)
	v_cvt_pk_bf16_f32 v1, v2, v3
	ds_read2_b32 v[2:3], v47 offset0:148 offset1:181
	s_waitcnt lgkmcnt(0)
	v_cvt_pk_bf16_f32 v2, v2, v3
	ds_read2_b32 v[34:35], v47 offset0:214 offset1:247
	s_waitcnt lgkmcnt(0)
	v_cvt_pk_bf16_f32 v3, v34, v35
	v_lshl_add_u64 v[38:39], v[36:37], 0, v[6:7]
	ds_read2_b32 v[34:35], v47 offset0:24 offset1:57
	global_store_dwordx4 v[38:39], v[0:3], off nt
	s_waitcnt lgkmcnt(0)
	s_nop 0
	v_cvt_pk_bf16_f32 v0, v34, v35
	ds_read2_b32 v[2:3], v47 offset0:90 offset1:123
	s_waitcnt lgkmcnt(0)
	v_cvt_pk_bf16_f32 v1, v2, v3
	ds_read2_b32 v[2:3], v47 offset0:156 offset1:189
	s_waitcnt lgkmcnt(0)
	v_cvt_pk_bf16_f32 v2, v2, v3
	v_or_b32_e32 v3, s9, v50
	ds_read2_b32 v[34:35], v47 offset0:222 offset1:255
	v_lshlrev_b32_e32 v6, 11, v3
	s_waitcnt lgkmcnt(0)
	v_cvt_pk_bf16_f32 v3, v34, v35
	v_lshl_add_u64 v[34:35], v[36:37], 0, v[6:7]
	global_store_dwordx4 v[34:35], v[0:3], off nt
	s_waitcnt lgkmcnt(0)

; __device__ __forceinline__ unsigned cvt_pk_bf16(float lo, float hi) { unsigned r; asm volatile("v_cvt_pk_bf16_f32 %0, %1, %2" : "=v"(r) : "v"(lo), "v"(hi)); return r; }
; template <int MAP>
; __device__ __forceinline__ void transpose_item(const float* __restrict__ W, int K, int N, bf16_t* __restrict__ WT, float* scr, int item, int lane) {
;     ...
;     for (int i = 0; i < 32; ++i) { const int kk = 2 * i + (lane >> 5); scr[kk * 33 + (lane & 31)] = __builtin_nontemporal_load(W + (size_t)(k0 + kk) * N + n0 + (lane & 31)); }
;     asm volatile("s_waitcnt lgkmcnt(0)" ::: "memory");
;     const int c = lane & 7;
; #pragma unroll
;     for (int j = 0; j < 4; ++j) { const int n = (lane >> 3) + 8 * j; const float* s = scr + (8 * c) * 33 + n;
;         u32x4 o; o.x = cvt_pk_bf16(s[0 * 33], s[1 * 33]); o.y = cvt_pk_bf16(s[2 * 33], s[3 * 33]); o.z = cvt_pk_bf16(s[4 * 33], s[5 * 33]); o.w = cvt_pk_bf16(s[6 * 33], s[7 * 33]);
;         if (MAP == 1) *(u32x4*)(WT + (size_t)row_map<MAP>(n0 + n) * K + k0 + 8 * c) = o;
; __device__ __forceinline__ void convert_weights(const Args& a, int l, unsigned char* lds, int gw, int NGW, int wave, int lane) {
;     ...
;         if (r < I_IN) { transpose_item<1>(w_in, DM, INC, (bf16_t*)(ws + WS_WIN), scr, r, lane); continue; } r -= I_IN;
.LBB0_66:
	v_lshl_add_u64 v[70:71], v[44:45], 0, s[12:13]
	v_lshl_add_u64 v[72:73], v[42:43], 0, s[12:13]
	v_lshl_add_u64 v[74:75], v[40:41], 0, s[12:13]
	v_lshl_add_u64 v[76:77], v[38:39], 0, s[12:13]
	v_lshl_add_u64 v[78:79], v[36:37], 0, s[12:13]
	v_lshl_add_u64 v[80:81], v[34:35], 0, s[12:13]
	v_lshl_add_u64 v[82:83], v[2:3], 0, s[12:13]
	v_lshl_add_u64 v[84:85], v[0:1], 0, s[12:13]
	global_load_dword v69, v[70:71], off nt
	global_load_dword v86, v[72:73], off nt
	global_load_dword v87, v[74:75], off nt
	global_load_dword v88, v[76:77], off nt
	global_load_dword v89, v[78:79], off nt
	global_load_dword v90, v[80:81], off nt
	global_load_dword v91, v[82:83], off nt
	global_load_dword v92, v[84:85], off nt
	s_add_u32 s12, s12, 0x88000
	s_addc_u32 s13, s13, 0
	v_add_u32_e32 v70, 0x400, v6
	s_cmp_eq_u32 s12, 0x220000
	v_lshl_add_u64 v[130:131], v[44:45], 0, s[12:13]
	v_lshl_add_u64 v[132:133], v[42:43], 0, s[12:13]
	v_lshl_add_u64 v[134:135], v[40:41], 0, s[12:13]
	v_lshl_add_u64 v[136:137], v[38:39], 0, s[12:13]
	v_lshl_add_u64 v[138:139], v[36:37], 0, s[12:13]
	v_lshl_add_u64 v[140:141], v[34:35], 0, s[12:13]
	v_lshl_add_u64 v[142:143], v[2:3], 0, s[12:13]
	v_lshl_add_u64 v[144:145], v[0:1], 0, s[12:13]
	global_load_dword v129, v[130:131], off nt
	global_load_dword v146, v[132:133], off nt
	global_load_dword v147, v[134:135], off nt
	global_load_dword v148, v[136:137], off nt
	global_load_dword v149, v[138:139], off nt
	global_load_dword v150, v[140:141], off nt
	global_load_dword v151, v[142:143], off nt
	global_load_dword v152, v[144:145], off nt
	s_add_u32 s12, s12, 0x88000
	s_addc_u32 s13, s13, 0
	v_add_u32_e32 v130, 0xc40, v6
	s_cmp_eq_u32 s12, 0x220000
	s_waitcnt vmcnt(14)
	ds_write2_b32 v6, v69, v86 offset1:66
	s_waitcnt vmcnt(12)
	ds_write2_b32 v6, v87, v88 offset0:132 offset1:198
	s_waitcnt vmcnt(10)
	ds_write2_b32 v70, v89, v90 offset0:8 offset1:74
	s_waitcnt vmcnt(8)
	ds_write2_b32 v70, v91, v92 offset0:140 offset1:206
	v_add_u32_e32 v6, 0x840, v6
	s_waitcnt vmcnt(6)
	ds_write2_b32 v6, v129, v146 offset1:66
	s_waitcnt vmcnt(4)
	ds_write2_b32 v6, v147, v148 offset0:132 offset1:198
	s_waitcnt vmcnt(2)
	ds_write2_b32 v130, v149, v150 offset0:8 offset1:74
	s_waitcnt vmcnt(0)
	ds_write2_b32 v130, v151, v152 offset0:140 offset1:206
	v_add_u32_e32 v6, 0x840, v6
	s_cbranch_scc0 .LBB0_66
	s_waitcnt lgkmcnt(0)
	ds_read2_b32 v[0:1], v47 offset1:33
	s_waitcnt lgkmcnt(0)
	v_cvt_pk_bf16_f32 v0, v0, v1
	ds_read2_b32 v[2:3], v47 offset0:66 offset1:99
	v_or_b32_e32 v6, s8, v46
	s_waitcnt lgkmcnt(0)
	v_cvt_pk_bf16_f32 v1, v2, v3
	ds_read2_b32 v[2:3], v47 offset0:132 offset1:165
	s_and_b32 s6, s8, 0x780
	v_cmp_lt_i32_e32 vcc, s26, v6
	s_waitcnt lgkmcnt(0)
	v_cvt_pk_bf16_f32 v2, v2, v3
	ds_read2_b32 v[34:35], v47 offset0:198 offset1:231
	s_waitcnt lgkmcnt(0)
	v_cvt_pk_bf16_f32 v3, v34, v35
	s_and_saveexec_b64 s[12:13], vcc
	s_xor_b64 s[12:13], exec, s[12:13]
	s_cbranch_execz .LBB0_89
	s_cmpk_gt_u32 s8, 0x4ff
	s_mov_b64 s[14:15], -1
	s_cbranch_scc0 .LBB0_86
	s_cmpk_gt_u32 s8, 0x5ff
	s_cbranch_scc0 .LBB0_83
	s_cmpk_gt_u32 s8, 0x9ff
	s_cbranch_scc0 .LBB0_80
	s_cmpk_gt_u32 s8, 0xdff
	s_cbranch_scc0 .LBB0_77
	s_cmpk_gt_u32 s8, 0x11ff
	s_cbranch_scc0 .LBB0_74
	v_add_u32_e32 v36, 0xfffffb00, v6
	s_mov_b64 s[14:15], 0

; __device__ __forceinline__ unsigned cvt_pk_bf16(float lo, float hi) { unsigned r; asm volatile("v_cvt_pk_bf16_f32 %0, %1, %2" : "=v"(r) : "v"(lo), "v"(hi)); return r; }
; template <int MAP>
; __device__ __forceinline__ void transpose_item(const float* __restrict__ W, int K, int N, bf16_t* __restrict__ WT, float* scr, int item, int lane) {
;     ...
; #pragma unroll 8
;     for (int i = 0; i < 32; ++i) { const int kk = 2 * i + (lane >> 5); scr[kk * 33 + (lane & 31)] = __builtin_nontemporal_load(W + (size_t)(k0 + kk) * N + n0 + (lane & 31)); }
;     asm volatile("s_waitcnt lgkmcnt(0)" ::: "memory");
;     const int c = lane & 7;
; #pragma unroll
;     for (int j = 0; j < 4; ++j) { const int n = (lane >> 3) + 8 * j; const float* s = scr + (8 * c) * 33 + n;
;         u32x4 o; o.x = cvt_pk_bf16(s[0 * 33], s[1 * 33]); o.y = cvt_pk_bf16(s[2 * 33], s[3 * 33]); o.z = cvt_pk_bf16(s[4 * 33], s[5 * 33]); o.w = cvt_pk_bf16(s[6 * 33], s[7 * 33]);
;         if (MAP == 1) *(u32x4*)(WT + (size_t)row_map<MAP>(n0 + n) * K + k0 + 8 * c) = o;
;         else __builtin_nontemporal_store(o, (u32x4*)(WT + (size_t)row_map<MAP>(n0 + n) * K + k0 + 8 * c)); }
.LBB0_241:
	v_lshl_add_u64 v[70:71], v[44:45], 0, s[0:1]
	v_lshl_add_u64 v[72:73], v[42:43], 0, s[0:1]
	v_lshl_add_u64 v[74:75], v[40:41], 0, s[0:1]
	v_lshl_add_u64 v[76:77], v[38:39], 0, s[0:1]
	v_lshl_add_u64 v[78:79], v[36:37], 0, s[0:1]
	v_lshl_add_u64 v[80:81], v[34:35], 0, s[0:1]
	v_lshl_add_u64 v[82:83], v[4:5], 0, s[0:1]
	v_lshl_add_u64 v[84:85], v[2:3], 0, s[0:1]
	global_load_dword v69, v[70:71], off nt
	s_nop 0
	global_load_dword v70, v[72:73], off nt
	global_load_dword v71, v[74:75], off nt
	s_nop 0
	global_load_dword v72, v[76:77], off nt
	global_load_dword v73, v[78:79], off nt
	global_load_dword v74, v[80:81], off nt
	global_load_dword v75, v[82:83], off nt
	s_nop 0
	global_load_dword v76, v[84:85], off nt
	s_add_u32 s0, s0, 0x20000
	s_addc_u32 s1, s1, 0
	v_add_u32_e32 v77, 0x400, v0
	s_cmp_lg_u32 s0, 0x80000
	v_lshl_add_u64 v[130:131], v[44:45], 0, s[0:1]
	v_lshl_add_u64 v[132:133], v[42:43], 0, s[0:1]
	v_lshl_add_u64 v[134:135], v[40:41], 0, s[0:1]
	v_lshl_add_u64 v[136:137], v[38:39], 0, s[0:1]
	v_lshl_add_u64 v[138:139], v[36:37], 0, s[0:1]
	v_lshl_add_u64 v[140:141], v[34:35], 0, s[0:1]
	v_lshl_add_u64 v[142:143], v[4:5], 0, s[0:1]
	v_lshl_add_u64 v[144:145], v[2:3], 0, s[0:1]
	global_load_dword v129, v[130:131], off nt
	s_nop 0
	global_load_dword v130, v[132:133], off nt
	global_load_dword v131, v[134:135], off nt
	s_nop 0
	global_load_dword v132, v[136:137], off nt
	global_load_dword v133, v[138:139], off nt
	global_load_dword v134, v[140:141], off nt
	global_load_dword v135, v[142:143], off nt
	s_nop 0
	global_load_dword v136, v[144:145], off nt
	s_add_u32 s0, s0, 0x20000
	s_addc_u32 s1, s1, 0
	v_add_u32_e32 v137, 0xc40, v0
	s_cmp_lg_u32 s0, 0x80000
	s_waitcnt vmcnt(14)
	ds_write2_b32 v0, v69, v70 offset1:66
	s_waitcnt vmcnt(12)
	ds_write2_b32 v0, v71, v72 offset0:132 offset1:198
	s_waitcnt vmcnt(10)
	ds_write2_b32 v77, v73, v74 offset0:8 offset1:74
	s_waitcnt vmcnt(8)
	ds_write2_b32 v77, v75, v76 offset0:140 offset1:206
	v_add_u32_e32 v0, 0x840, v0
	s_waitcnt vmcnt(6)
	ds_write2_b32 v0, v129, v130 offset1:66
	s_waitcnt vmcnt(4)
	ds_write2_b32 v0, v131, v132 offset0:132 offset1:198
	s_waitcnt vmcnt(2)
	ds_write2_b32 v137, v133, v134 offset0:8 offset1:74
	s_waitcnt vmcnt(0)
	ds_write2_b32 v137, v135, v136 offset0:140 offset1:206
	v_add_u32_e32 v0, 0x840, v0
	s_cbranch_scc1 .LBB0_241
	s_add_i32 s0, s18, 0xffffa200
	s_and_b32 s1, s0, 0x1fc0
	s_lshl_b32 s0, s0, 5
	s_waitcnt lgkmcnt(0)
	s_and_b32 s0, s0, 0x7e0
	ds_read2_b32 v[2:3], v47 offset1:33
	v_or_b32_e32 v0, s0, v46
	s_waitcnt lgkmcnt(0)
	v_cvt_pk_bf16_f32 v2, v2, v3
	ds_read2_b32 v[4:5], v47 offset0:66 offset1:99
	s_lshl_b32 s60, s1, 1
	v_mul_u32_u24_e32 v0, 0x1600, v0
	s_waitcnt lgkmcnt(0)
	v_cvt_pk_bf16_f32 v3, v4, v5
	ds_read2_b32 v[4:5], v47 offset0:132 offset1:165
	v_lshl_add_u64 v[36:37], v[8:9], 0, s[60:61]
	v_lshlrev_b32_e32 v0, 1, v0
	s_waitcnt lgkmcnt(0)
	v_cvt_pk_bf16_f32 v4, v4, v5
	ds_read2_b32 v[34:35], v47 offset0:198 offset1:231
	s_waitcnt lgkmcnt(0)
	v_cvt_pk_bf16_f32 v5, v34, v35
	v_lshl_add_u64 v[38:39], v[36:37], 0, v[0:1]
	v_or_b32_e32 v0, s0, v48
	ds_read2_b32 v[34:35], v47 offset0:8 offset1:41
	global_store_dwordx4 v[38:39], v[2:5], off nt
	v_mul_u32_u24_e32 v0, 0x1600, v0
	v_lshlrev_b32_e32 v0, 1, v0
	s_waitcnt lgkmcnt(0)
	v_cvt_pk_bf16_f32 v2, v34, v35
	ds_read2_b32 v[4:5], v47 offset0:74 offset1:107
	s_waitcnt lgkmcnt(0)
	v_cvt_pk_bf16_f32 v3, v4, v5
	ds_read2_b32 v[4:5], v47 offset0:140 offset1:173
	s_waitcnt lgkmcnt(0)
	v_cvt_pk_bf16_f32 v4, v4, v5
	ds_read2_b32 v[34:35], v47 offset0:206 offset1:239
	s_waitcnt lgkmcnt(0)
	v_cvt_pk_bf16_f32 v5, v34, v35
	v_lshl_add_u64 v[38:39], v[36:37], 0, v[0:1]
	v_or_b32_e32 v0, s0, v49
	ds_read2_b32 v[34:35], v47 offset0:16 offset1:49
	global_store_dwordx4 v[38:39], v[2:5], off nt
	v_mul_u32_u24_e32 v0, 0x1600, v0
	v_lshlrev_b32_e32 v0, 1, v0
	s_waitcnt lgkmcnt(0)
	v_cvt_pk_bf16_f32 v2, v34, v35
	ds_read2_b32 v[4:5], v47 offset0:82 offset1:115
	s_waitcnt lgkmcnt(0)
	v_cvt_pk_bf16_f32 v3, v4, v5
	ds_read2_b32 v[4:5], v47 offset0:148 offset1:181
	s_waitcnt lgkmcnt(0)
	v_cvt_pk_bf16_f32 v4, v4, v5
	ds_read2_b32 v[34:35], v47 offset0:214 offset1:247
	s_waitcnt lgkmcnt(0)
	v_cvt_pk_bf16_f32 v5, v34, v35
	v_lshl_add_u64 v[38:39], v[36:37], 0, v[0:1]
	ds_read2_b32 v[34:35], v47 offset0:24 offset1:57
	global_store_dwordx4 v[38:39], v[2:5], off nt
	v_or_b32_e32 v0, s0, v50
	v_mul_u32_u24_e32 v0, 0x1600, v0
	s_waitcnt lgkmcnt(0)
	v_cvt_pk_bf16_f32 v2, v34, v35
	ds_read2_b32 v[4:5], v47 offset0:90 offset1:123
	s_waitcnt lgkmcnt(0)
	v_cvt_pk_bf16_f32 v3, v4, v5
	ds_read2_b32 v[4:5], v47 offset0:156 offset1:189
	s_waitcnt lgkmcnt(0)
	v_cvt_pk_bf16_f32 v4, v4, v5
	ds_read2_b32 v[34:35], v47 offset0:222 offset1:255
	v_lshlrev_b32_e32 v0, 1, v0
	s_waitcnt lgkmcnt(0)
	v_cvt_pk_bf16_f32 v5, v34, v35
	v_lshl_add_u64 v[34:35], v[36:37], 0, v[0:1]
	global_store_dwordx4 v[34:35], v[2:5], off nt
	s_waitcnt lgkmcnt(0)
	s_mov_b64 s[0:1], 0

; __device__ __forceinline__ unsigned cvt_pk_bf16(float lo, float hi) { unsigned r; asm volatile("v_cvt_pk_bf16_f32 %0, %1, %2" : "=v"(r) : "v"(lo), "v"(hi)); return r; }
; template <int MAP>
; __device__ __forceinline__ int row_map(int n) {
;     ...
;     if (MAP == 2) { const int c = n < FF ? n : n - FF; return 256 * (c >> 7) + (c & 127) + (n < FF ? 0 : 128); }
; template <int MAP>
; __device__ __forceinline__ void transpose_item(const float* __restrict__ W, int K, int N, bf16_t* __restrict__ WT, float* scr, int item, int lane) {
;     ...
; #pragma unroll 8
;     for (int i = 0; i < 32; ++i) { const int kk = 2 * i + (lane >> 5); scr[kk * 33 + (lane & 31)] = __builtin_nontemporal_load(W + (size_t)(k0 + kk) * N + n0 + (lane & 31)); }
;     asm volatile("s_waitcnt lgkmcnt(0)" ::: "memory");
;     const int c = lane & 7;
; #pragma unroll
;     for (int j = 0; j < 4; ++j) { const int n = (lane >> 3) + 8 * j; const float* s = scr + (8 * c) * 33 + n;
;         u32x4 o; o.x = cvt_pk_bf16(s[0 * 33], s[1 * 33]); o.y = cvt_pk_bf16(s[2 * 33], s[3 * 33]); o.z = cvt_pk_bf16(s[4 * 33], s[5 * 33]); o.w = cvt_pk_bf16(s[6 * 33], s[7 * 33]);
;         if (MAP == 1) *(u32x4*)(WT + (size_t)row_map<MAP>(n0 + n) * K + k0 + 8 * c) = o;
;         else __builtin_nontemporal_store(o, (u32x4*)(WT + (size_t)row_map<MAP>(n0 + n) * K + k0 + 8 * c)); }
.LBB0_245:
	v_lshl_add_u64 v[44:45], v[38:39], 0, s[12:13]
	v_add_co_u32_e32 v78, vcc, 0x5816000, v44
	v_lshl_add_u64 v[42:43], v[40:41], 0, s[12:13]
	v_lshl_add_u64 v[70:71], v[36:37], 0, s[12:13]
	v_lshl_add_u64 v[72:73], v[34:35], 0, s[12:13]
	s_mov_b64 s[0:1], vcc
	v_lshl_add_u64 v[74:75], v[4:5], 0, s[12:13]
	v_lshl_add_u64 v[76:77], v[2:3], 0, s[12:13]
	global_load_dword v69, v[42:43], off nt
	s_nop 0
	global_load_dword v70, v[70:71], off nt
	s_nop 0
	global_load_dword v71, v[72:73], off nt
	s_nop 0
	global_load_dword v72, v[74:75], off nt
	global_load_dword v73, v[76:77], off nt
	v_add_co_u32_e32 v42, vcc, 0x582c000, v44
	v_addc_co_u32_e64 v79, s[0:1], 0, v45, s[0:1]
	s_mov_b64 s[0:1], vcc
	v_add_co_u32_e32 v44, vcc, 0x5842000, v44
	v_addc_co_u32_e64 v43, s[0:1], 0, v45, s[0:1]
	global_load_dword v74, v[78:79], off nt
	v_addc_co_u32_e32 v45, vcc, 0, v45, vcc
	global_load_dword v42, v[42:43], off nt
	s_nop 0
	global_load_dword v43, v[44:45], off nt
	s_add_u32 s12, s12, 0xb0000
	v_add_u32_e32 v44, 0x400, v0
	s_addc_u32 s13, s13, 0
	s_cmp_lg_u32 s12, 0x2c0000
	v_lshl_add_u64 v[104:105], v[38:39], 0, s[12:13]
	v_add_co_u32_e32 v138, vcc, 0x5816000, v104
	v_lshl_add_u64 v[102:103], v[40:41], 0, s[12:13]
	v_lshl_add_u64 v[130:131], v[36:37], 0, s[12:13]
	v_lshl_add_u64 v[132:133], v[34:35], 0, s[12:13]
	s_mov_b64 s[0:1], vcc
	v_lshl_add_u64 v[134:135], v[4:5], 0, s[12:13]
	v_lshl_add_u64 v[136:137], v[2:3], 0, s[12:13]
	global_load_dword v129, v[102:103], off nt
	s_nop 0
	global_load_dword v130, v[130:131], off nt
	s_nop 0
	global_load_dword v131, v[132:133], off nt
	s_nop 0
	global_load_dword v132, v[134:135], off nt
	global_load_dword v133, v[136:137], off nt
	v_add_co_u32_e32 v102, vcc, 0x582c000, v104
	v_addc_co_u32_e64 v139, s[0:1], 0, v105, s[0:1]
	s_mov_b64 s[0:1], vcc
	v_add_co_u32_e32 v104, vcc, 0x5842000, v104
	v_addc_co_u32_e64 v103, s[0:1], 0, v105, s[0:1]
	global_load_dword v134, v[138:139], off nt
	v_addc_co_u32_e32 v105, vcc, 0, v105, vcc
	global_load_dword v102, v[102:103], off nt
	s_nop 0
	global_load_dword v103, v[104:105], off nt
	s_add_u32 s12, s12, 0xb0000
	v_add_u32_e32 v104, 0xc40, v0
	s_addc_u32 s13, s13, 0
	s_cmp_lg_u32 s12, 0x2c0000
	s_waitcnt vmcnt(13)
	ds_write2_b32 v44, v70, v71 offset0:8 offset1:74
	s_waitcnt vmcnt(11)
	ds_write2_b32 v44, v72, v73 offset0:140 offset1:206
	s_waitcnt vmcnt(10)
	ds_write2_b32 v0, v69, v74 offset1:66
	s_waitcnt vmcnt(8)
	ds_write2_b32 v0, v42, v43 offset0:132 offset1:198
	v_add_u32_e32 v0, 0x840, v0
	s_waitcnt vmcnt(5)
	ds_write2_b32 v104, v130, v131 offset0:8 offset1:74
	s_waitcnt vmcnt(3)
	ds_write2_b32 v104, v132, v133 offset0:140 offset1:206
	s_waitcnt vmcnt(2)
	ds_write2_b32 v0, v129, v134 offset1:66
	s_waitcnt vmcnt(0)
	ds_write2_b32 v0, v102, v103 offset0:132 offset1:198
	v_add_u32_e32 v0, 0x840, v0
	s_cbranch_scc1 .LBB0_245
	s_and_b32 s0, 0xffff, s15
	s_waitcnt lgkmcnt(0)
	s_and_b32 s12, 0xffff, s16
	s_and_b32 s1, 0xffff, s14
	s_lshl_b32 s60, s0, 1
	ds_read2_b32 v[2:3], v47 offset1:33
	v_or_b32_e32 v0, s12, v46
	s_cmpk_lt_u32 s1, 0xb0
	s_waitcnt lgkmcnt(0)
	v_cvt_pk_bf16_f32 v2, v2, v3
	ds_read2_b32 v[4:5], v47 offset0:66 offset1:99
	v_add_u32_e32 v38, 0xffffea00, v0
	s_cselect_b64 vcc, -1, 0
	s_waitcnt lgkmcnt(0)
	v_cvt_pk_bf16_f32 v3, v4, v5
	ds_read2_b32 v[4:5], v47 offset0:132 offset1:165
	v_cndmask_b32_e32 v0, v38, v0, vcc
	s_waitcnt lgkmcnt(0)
	v_cvt_pk_bf16_f32 v4, v4, v5
	v_lshlrev_b32_e32 v5, 1, v0
	s_and_b64 s[0:1], vcc, exec
	ds_read2_b32 v[36:37], v47 offset0:198 offset1:231
	v_and_b32_e32 v0, 0x67, v0
	v_and_b32_e32 v38, 0xffffff00, v5
	s_cselect_b32 s0, 0, 0x80
	s_waitcnt lgkmcnt(0)
	v_cvt_pk_bf16_f32 v5, v36, v37
	v_or3_b32 v36, v0, v38, s0
	v_ashrrev_i32_e32 v37, 31, v36
	v_lshl_add_u64 v[34:35], v[10:11], 0, s[60:61]
	v_lshlrev_b64 v[36:37], 12, v[36:37]
	v_lshl_add_u64 v[36:37], v[34:35], 0, v[36:37]
	ds_read2_b32 v[38:39], v47 offset0:8 offset1:41
	global_store_dwordx4 v[36:37], v[2:5], off nt
	v_or_b32_e32 v0, s12, v48
	s_waitcnt lgkmcnt(0)
	v_cvt_pk_bf16_f32 v2, v38, v39
	ds_read2_b32 v[4:5], v47 offset0:74 offset1:107
	s_waitcnt lgkmcnt(0)
	v_cvt_pk_bf16_f32 v3, v4, v5
	ds_read2_b32 v[4:5], v47 offset0:140 offset1:173
	s_waitcnt lgkmcnt(0)
	v_cvt_pk_bf16_f32 v4, v4, v5
	v_add_u32_e32 v5, 0xffffea00, v0
	v_cndmask_b32_e32 v0, v5, v0, vcc
	v_lshlrev_b32_e32 v5, 1, v0
	ds_read2_b32 v[36:37], v47 offset0:206 offset1:239
	v_and_b32_e32 v38, 0xffffff00, v5
	v_and_b32_e32 v0, 0x6f, v0
	s_waitcnt lgkmcnt(0)
	v_cvt_pk_bf16_f32 v5, v36, v37
	v_or3_b32 v36, v0, v38, s0
	v_ashrrev_i32_e32 v37, 31, v36
	v_lshlrev_b64 v[36:37], 12, v[36:37]
	ds_read2_b32 v[38:39], v47 offset0:16 offset1:49
	v_lshl_add_u64 v[36:37], v[34:35], 0, v[36:37]
	v_or_b32_e32 v0, s12, v49
	global_store_dwordx4 v[36:37], v[2:5], off nt
	s_waitcnt lgkmcnt(0)
	s_nop 0
	v_cvt_pk_bf16_f32 v2, v38, v39
	ds_read2_b32 v[4:5], v47 offset0:82 offset1:115
	v_add_u32_e32 v38, 0xffffea00, v0
	s_waitcnt lgkmcnt(0)
	v_cvt_pk_bf16_f32 v3, v4, v5
	ds_read2_b32 v[4:5], v47 offset0:148 offset1:181
	v_cndmask_b32_e32 v0, v38, v0, vcc
	s_waitcnt lgkmcnt(0)
	v_cvt_pk_bf16_f32 v4, v4, v5
	v_lshlrev_b32_e32 v5, 1, v0
	ds_read2_b32 v[36:37], v47 offset0:214 offset1:247
	v_and_b32_e32 v0, 0x77, v0
	v_and_b32_e32 v38, 0xffffff00, v5
	s_waitcnt lgkmcnt(0)
	v_cvt_pk_bf16_f32 v5, v36, v37
	v_or3_b32 v36, v0, v38, s0
	v_ashrrev_i32_e32 v37, 31, v36
	v_lshlrev_b64 v[36:37], 12, v[36:37]
	v_lshl_add_u64 v[36:37], v[34:35], 0, v[36:37]
	v_or_b32_e32 v0, s12, v50
	ds_read2_b32 v[38:39], v47 offset0:24 offset1:57
	global_store_dwordx4 v[36:37], v[2:5], off nt
	v_add_u32_e32 v36, 0xffffea00, v0
	v_cndmask_b32_e32 v0, v36, v0, vcc
	s_waitcnt lgkmcnt(0)
	v_cvt_pk_bf16_f32 v2, v38, v39
	ds_read2_b32 v[4:5], v47 offset0:90 offset1:123
	s_waitcnt lgkmcnt(0)
	v_cvt_pk_bf16_f32 v3, v4, v5
	ds_read2_b32 v[4:5], v47 offset0:156 offset1:189
	s_waitcnt lgkmcnt(0)
	v_cvt_pk_bf16_f32 v4, v4, v5
	v_lshlrev_b32_e32 v5, 1, v0
	v_and_b32_e32 v0, 0x7f, v0
	v_and_b32_e32 v5, 0xffffff00, v5
	v_or3_b32 v38, v0, v5, s0
	ds_read2_b32 v[36:37], v47 offset0:222 offset1:255
	v_ashrrev_i32_e32 v39, 31, v38
	s_waitcnt lgkmcnt(0)
	v_cvt_pk_bf16_f32 v5, v36, v37
	v_lshlrev_b64 v[36:37], 12, v[38:39]
	v_lshl_add_u64 v[34:35], v[34:35], 0, v[36:37]
	global_store_dwordx4 v[34:35], v[2:5], off nt
	s_waitcnt lgkmcnt(0)

; __device__ __forceinline__ unsigned cvt_pk_bf16(float lo, float hi) { unsigned r; asm volatile("v_cvt_pk_bf16_f32 %0, %1, %2" : "=v"(r) : "v"(lo), "v"(hi)); return r; }
; template <int MAP>
; __device__ __forceinline__ void transpose_item(const float* __restrict__ W, int K, int N, bf16_t* __restrict__ WT, float* scr, int item, int lane) {
;     ...
; #pragma unroll 8
;     for (int i = 0; i < 32; ++i) { const int kk = 2 * i + (lane >> 5); scr[kk * 33 + (lane & 31)] = __builtin_nontemporal_load(W + (size_t)(k0 + kk) * N + n0 + (lane & 31)); }
;     asm volatile("s_waitcnt lgkmcnt(0)" ::: "memory");
;     const int c = lane & 7;
; #pragma unroll
;     for (int j = 0; j < 4; ++j) { const int n = (lane >> 3) + 8 * j; const float* s = scr + (8 * c) * 33 + n;
;         u32x4 o; o.x = cvt_pk_bf16(s[0 * 33], s[1 * 33]); o.y = cvt_pk_bf16(s[2 * 33], s[3 * 33]); o.z = cvt_pk_bf16(s[4 * 33], s[5 * 33]); o.w = cvt_pk_bf16(s[6 * 33], s[7 * 33]);
;         if (MAP == 1) *(u32x4*)(WT + (size_t)row_map<MAP>(n0 + n) * K + k0 + 8 * c) = o;
;         else __builtin_nontemporal_store(o, (u32x4*)(WT + (size_t)row_map<MAP>(n0 + n) * K + k0 + 8 * c)); }
.LBB0_250:
	v_lshl_add_u64 v[70:71], v[44:45], 0, s[0:1]
	v_lshl_add_u64 v[72:73], v[42:43], 0, s[0:1]
	v_lshl_add_u64 v[74:75], v[40:41], 0, s[0:1]
	v_lshl_add_u64 v[76:77], v[38:39], 0, s[0:1]
	v_lshl_add_u64 v[78:79], v[36:37], 0, s[0:1]
	v_lshl_add_u64 v[80:81], v[34:35], 0, s[0:1]
	v_lshl_add_u64 v[82:83], v[4:5], 0, s[0:1]
	v_lshl_add_u64 v[84:85], v[2:3], 0, s[0:1]
	global_load_dword v69, v[70:71], off nt
	s_nop 0
	global_load_dword v70, v[72:73], off nt
	global_load_dword v71, v[74:75], off nt
	s_nop 0
	global_load_dword v72, v[76:77], off nt
	global_load_dword v73, v[78:79], off nt
	global_load_dword v74, v[80:81], off nt
	global_load_dword v75, v[82:83], off nt
	s_nop 0
	global_load_dword v76, v[84:85], off nt
	s_add_u32 s0, s0, 0x20000
	s_addc_u32 s1, s1, 0
	v_add_u32_e32 v77, 0x400, v0
	s_cmp_lg_u32 s0, 0x80000
	v_lshl_add_u64 v[130:131], v[44:45], 0, s[0:1]
	v_lshl_add_u64 v[132:133], v[42:43], 0, s[0:1]
	v_lshl_add_u64 v[134:135], v[40:41], 0, s[0:1]
	v_lshl_add_u64 v[136:137], v[38:39], 0, s[0:1]
	v_lshl_add_u64 v[138:139], v[36:37], 0, s[0:1]
	v_lshl_add_u64 v[140:141], v[34:35], 0, s[0:1]
	v_lshl_add_u64 v[142:143], v[4:5], 0, s[0:1]
	v_lshl_add_u64 v[144:145], v[2:3], 0, s[0:1]
	global_load_dword v129, v[130:131], off nt
	s_nop 0
	global_load_dword v130, v[132:133], off nt
	global_load_dword v131, v[134:135], off nt
	s_nop 0
	global_load_dword v132, v[136:137], off nt
	global_load_dword v133, v[138:139], off nt
	global_load_dword v134, v[140:141], off nt
	global_load_dword v135, v[142:143], off nt
	s_nop 0
	global_load_dword v136, v[144:145], off nt
	s_add_u32 s0, s0, 0x20000
	s_addc_u32 s1, s1, 0
	v_add_u32_e32 v137, 0xc40, v0
	s_cmp_lg_u32 s0, 0x80000
	s_waitcnt vmcnt(14)
	ds_write2_b32 v0, v69, v70 offset1:66
	s_waitcnt vmcnt(12)
	ds_write2_b32 v0, v71, v72 offset0:132 offset1:198
	s_waitcnt vmcnt(10)
	ds_write2_b32 v77, v73, v74 offset0:8 offset1:74
	s_waitcnt vmcnt(8)
	ds_write2_b32 v77, v75, v76 offset0:140 offset1:206
	v_add_u32_e32 v0, 0x840, v0
	s_waitcnt vmcnt(6)
	ds_write2_b32 v0, v129, v130 offset1:66
	s_waitcnt vmcnt(4)
	ds_write2_b32 v0, v131, v132 offset0:132 offset1:198
	s_waitcnt vmcnt(2)
	ds_write2_b32 v137, v133, v134 offset0:8 offset1:74
	s_waitcnt vmcnt(0)
	ds_write2_b32 v137, v135, v136 offset0:140 offset1:206
	v_add_u32_e32 v0, 0x840, v0
	s_cbranch_scc1 .LBB0_250
	s_add_i32 s0, s18, 0xffffd600
	s_waitcnt lgkmcnt(0)
	s_and_b32 s1, s0, 0x1fc0
	s_lshl_b32 s0, s0, 5
	ds_read2_b32 v[2:3], v47 offset1:33
	s_and_b32 s0, s0, 0x7e0
	s_waitcnt lgkmcnt(0)
	v_cvt_pk_bf16_f32 v2, v2, v3
	ds_read2_b32 v[4:5], v47 offset0:66 offset1:99
	s_lshl_b32 s60, s1, 1
	v_or_b32_e32 v0, s0, v46
	s_waitcnt lgkmcnt(0)
	v_cvt_pk_bf16_f32 v3, v4, v5
	ds_read2_b32 v[4:5], v47 offset0:132 offset1:165
	v_lshl_add_u64 v[36:37], v[12:13], 0, s[60:61]
	v_lshlrev_b32_e32 v0, 12, v0
	s_waitcnt lgkmcnt(0)
	v_cvt_pk_bf16_f32 v4, v4, v5
	ds_read2_b32 v[34:35], v47 offset0:198 offset1:231
	s_waitcnt lgkmcnt(0)
	v_cvt_pk_bf16_f32 v5, v34, v35
	v_lshl_add_u64 v[38:39], v[36:37], 0, v[0:1]
	ds_read2_b32 v[34:35], v47 offset0:8 offset1:41
	global_store_dwordx4 v[38:39], v[2:5], off nt
	v_or_b32_e32 v0, s0, v48
	v_lshlrev_b32_e32 v0, 12, v0
	s_waitcnt lgkmcnt(0)
	v_cvt_pk_bf16_f32 v2, v34, v35
	ds_read2_b32 v[4:5], v47 offset0:74 offset1:107
	s_waitcnt lgkmcnt(0)
	v_cvt_pk_bf16_f32 v3, v4, v5
	ds_read2_b32 v[4:5], v47 offset0:140 offset1:173
	s_waitcnt lgkmcnt(0)
	v_cvt_pk_bf16_f32 v4, v4, v5
	ds_read2_b32 v[34:35], v47 offset0:206 offset1:239
	s_waitcnt lgkmcnt(0)
	v_cvt_pk_bf16_f32 v5, v34, v35
	v_lshl_add_u64 v[38:39], v[36:37], 0, v[0:1]
	ds_read2_b32 v[34:35], v47 offset0:16 offset1:49
	global_store_dwordx4 v[38:39], v[2:5], off nt
	v_or_b32_e32 v0, s0, v49
	v_lshlrev_b32_e32 v0, 12, v0
	s_waitcnt lgkmcnt(0)
	v_cvt_pk_bf16_f32 v2, v34, v35
	ds_read2_b32 v[4:5], v47 offset0:82 offset1:115
	s_waitcnt lgkmcnt(0)
	v_cvt_pk_bf16_f32 v3, v4, v5
	ds_read2_b32 v[4:5], v47 offset0:148 offset1:181
	s_waitcnt lgkmcnt(0)
	v_cvt_pk_bf16_f32 v4, v4, v5
	ds_read2_b32 v[34:35], v47 offset0:214 offset1:247
	s_waitcnt lgkmcnt(0)
	v_cvt_pk_bf16_f32 v5, v34, v35
	v_lshl_add_u64 v[38:39], v[36:37], 0, v[0:1]
	ds_read2_b32 v[34:35], v47 offset0:24 offset1:57
	global_store_dwordx4 v[38:39], v[2:5], off nt
	v_or_b32_e32 v0, s0, v50
	v_lshlrev_b32_e32 v0, 12, v0
	s_waitcnt lgkmcnt(0)
	v_cvt_pk_bf16_f32 v2, v34, v35
	ds_read2_b32 v[4:5], v47 offset0:90 offset1:123
	s_waitcnt lgkmcnt(0)
	v_cvt_pk_bf16_f32 v3, v4, v5
	ds_read2_b32 v[4:5], v47 offset0:156 offset1:189
	s_waitcnt lgkmcnt(0)
	v_cvt_pk_bf16_f32 v4, v4, v5
	ds_read2_b32 v[34:35], v47 offset0:222 offset1:255
	s_waitcnt lgkmcnt(0)
	v_cvt_pk_bf16_f32 v5, v34, v35
	v_lshl_add_u64 v[34:35], v[36:37], 0, v[0:1]
	global_store_dwordx4 v[34:35], v[2:5], off nt
	s_waitcnt lgkmcnt(0)

; __device__ __forceinline__ unsigned cvt_pk_bf16(float lo, float hi) { unsigned r; asm volatile("v_cvt_pk_bf16_f32 %0, %1, %2" : "=v"(r) : "v"(lo), "v"(hi)); return r; }
; template <int MAP>
; __device__ __forceinline__ void transpose_item(const float* __restrict__ W, int K, int N, bf16_t* __restrict__ WT, float* scr, int item, int lane) {
;     ...
; #pragma unroll 8
;     for (int i = 0; i < 32; ++i) { const int kk = 2 * i + (lane >> 5); scr[kk * 33 + (lane & 31)] = __builtin_nontemporal_load(W + (size_t)(k0 + kk) * N + n0 + (lane & 31)); }
;     asm volatile("s_waitcnt lgkmcnt(0)" ::: "memory");
;     const int c = lane & 7;
; #pragma unroll
;     for (int j = 0; j < 4; ++j) { const int n = (lane >> 3) + 8 * j; const float* s = scr + (8 * c) * 33 + n;
;         u32x4 o; o.x = cvt_pk_bf16(s[0 * 33], s[1 * 33]); o.y = cvt_pk_bf16(s[2 * 33], s[3 * 33]); o.z = cvt_pk_bf16(s[4 * 33], s[5 * 33]); o.w = cvt_pk_bf16(s[6 * 33], s[7 * 33]);
;         if (MAP == 1) *(u32x4*)(WT + (size_t)row_map<MAP>(n0 + n) * K + k0 + 8 * c) = o;
;         else __builtin_nontemporal_store(o, (u32x4*)(WT + (size_t)row_map<MAP>(n0 + n) * K + k0 + 8 * c)); }
.LBB0_255:
	v_lshl_add_u64 v[70:71], v[44:45], 0, s[0:1]
	v_lshl_add_u64 v[72:73], v[42:43], 0, s[0:1]
	v_lshl_add_u64 v[74:75], v[40:41], 0, s[0:1]
	v_lshl_add_u64 v[76:77], v[38:39], 0, s[0:1]
	v_lshl_add_u64 v[78:79], v[36:37], 0, s[0:1]
	v_lshl_add_u64 v[80:81], v[34:35], 0, s[0:1]
	v_lshl_add_u64 v[82:83], v[4:5], 0, s[0:1]
	v_lshl_add_u64 v[84:85], v[2:3], 0, s[0:1]
	global_load_dword v69, v[70:71], off nt
	s_nop 0
	global_load_dword v70, v[72:73], off nt
	global_load_dword v71, v[74:75], off nt
	s_nop 0
	global_load_dword v72, v[76:77], off nt
	global_load_dword v73, v[78:79], off nt
	global_load_dword v74, v[80:81], off nt
	global_load_dword v75, v[82:83], off nt
	s_nop 0
	global_load_dword v76, v[84:85], off nt
	s_add_u32 s0, s0, 0x20000
	s_addc_u32 s1, s1, 0
	v_add_u32_e32 v77, 0x400, v0
	s_cmp_lg_u32 s0, 0x80000
	v_lshl_add_u64 v[130:131], v[44:45], 0, s[0:1]
	v_lshl_add_u64 v[132:133], v[42:43], 0, s[0:1]
	v_lshl_add_u64 v[134:135], v[40:41], 0, s[0:1]
	v_lshl_add_u64 v[136:137], v[38:39], 0, s[0:1]
	v_lshl_add_u64 v[138:139], v[36:37], 0, s[0:1]
	v_lshl_add_u64 v[140:141], v[34:35], 0, s[0:1]
	v_lshl_add_u64 v[142:143], v[4:5], 0, s[0:1]
	v_lshl_add_u64 v[144:145], v[2:3], 0, s[0:1]
	global_load_dword v129, v[130:131], off nt
	s_nop 0
	global_load_dword v130, v[132:133], off nt
	global_load_dword v131, v[134:135], off nt
	s_nop 0
	global_load_dword v132, v[136:137], off nt
	global_load_dword v133, v[138:139], off nt
	global_load_dword v134, v[140:141], off nt
	global_load_dword v135, v[142:143], off nt
	s_nop 0
	global_load_dword v136, v[144:145], off nt
	s_add_u32 s0, s0, 0x20000
	s_addc_u32 s1, s1, 0
	v_add_u32_e32 v137, 0xc40, v0
	s_cmp_lg_u32 s0, 0x80000
	s_waitcnt vmcnt(14)
	ds_write2_b32 v0, v69, v70 offset1:66
	s_waitcnt vmcnt(12)
	ds_write2_b32 v0, v71, v72 offset0:132 offset1:198
	s_waitcnt vmcnt(10)
	ds_write2_b32 v77, v73, v74 offset0:8 offset1:74
	s_waitcnt vmcnt(8)
	ds_write2_b32 v77, v75, v76 offset0:140 offset1:206
	v_add_u32_e32 v0, 0x840, v0
	s_waitcnt vmcnt(6)
	ds_write2_b32 v0, v129, v130 offset1:66
	s_waitcnt vmcnt(4)
	ds_write2_b32 v0, v131, v132 offset0:132 offset1:198
	s_waitcnt vmcnt(2)
	ds_write2_b32 v137, v133, v134 offset0:8 offset1:74
	s_waitcnt vmcnt(0)
	ds_write2_b32 v137, v135, v136 offset0:140 offset1:206
	v_add_u32_e32 v0, 0x840, v0
	s_cbranch_scc1 .LBB0_255
	s_add_i32 s0, s18, 0xffffda00
	s_waitcnt lgkmcnt(0)
	s_and_b32 s1, s0, 0x1fc0
	s_lshl_b32 s0, s0, 5
	ds_read2_b32 v[2:3], v47 offset1:33
	s_and_b32 s0, s0, 0x7e0
	s_waitcnt lgkmcnt(0)
	v_cvt_pk_bf16_f32 v2, v2, v3
	ds_read2_b32 v[4:5], v47 offset0:66 offset1:99
	s_lshl_b32 s60, s1, 1
	v_or_b32_e32 v0, s0, v46
	s_waitcnt lgkmcnt(0)
	v_cvt_pk_bf16_f32 v3, v4, v5
	ds_read2_b32 v[4:5], v47 offset0:132 offset1:165
	v_lshl_add_u64 v[36:37], v[14:15], 0, s[60:61]
	v_lshlrev_b32_e32 v0, 11, v0
	s_waitcnt lgkmcnt(0)
	v_cvt_pk_bf16_f32 v4, v4, v5
	ds_read2_b32 v[34:35], v47 offset0:198 offset1:231
	s_waitcnt lgkmcnt(0)
	v_cvt_pk_bf16_f32 v5, v34, v35
	v_lshl_add_u64 v[38:39], v[36:37], 0, v[0:1]
	ds_read2_b32 v[34:35], v47 offset0:8 offset1:41
	global_store_dwordx4 v[38:39], v[2:5], off nt
	v_or_b32_e32 v0, s0, v48
	v_lshlrev_b32_e32 v0, 11, v0
	s_waitcnt lgkmcnt(0)
	v_cvt_pk_bf16_f32 v2, v34, v35
	ds_read2_b32 v[4:5], v47 offset0:74 offset1:107
	s_waitcnt lgkmcnt(0)
	v_cvt_pk_bf16_f32 v3, v4, v5
	ds_read2_b32 v[4:5], v47 offset0:140 offset1:173
	s_waitcnt lgkmcnt(0)
	v_cvt_pk_bf16_f32 v4, v4, v5
	ds_read2_b32 v[34:35], v47 offset0:206 offset1:239
	s_waitcnt lgkmcnt(0)
	v_cvt_pk_bf16_f32 v5, v34, v35
	v_lshl_add_u64 v[38:39], v[36:37], 0, v[0:1]
	ds_read2_b32 v[34:35], v47 offset0:16 offset1:49
	global_store_dwordx4 v[38:39], v[2:5], off nt
	v_or_b32_e32 v0, s0, v49
	v_lshlrev_b32_e32 v0, 11, v0
	s_waitcnt lgkmcnt(0)
	v_cvt_pk_bf16_f32 v2, v34, v35
	ds_read2_b32 v[4:5], v47 offset0:82 offset1:115
	s_waitcnt lgkmcnt(0)
	v_cvt_pk_bf16_f32 v3, v4, v5
	ds_read2_b32 v[4:5], v47 offset0:148 offset1:181
	s_waitcnt lgkmcnt(0)
	v_cvt_pk_bf16_f32 v4, v4, v5
	ds_read2_b32 v[34:35], v47 offset0:214 offset1:247
	s_waitcnt lgkmcnt(0)
	v_cvt_pk_bf16_f32 v5, v34, v35
	v_lshl_add_u64 v[38:39], v[36:37], 0, v[0:1]
	ds_read2_b32 v[34:35], v47 offset0:24 offset1:57
	global_store_dwordx4 v[38:39], v[2:5], off nt
	v_or_b32_e32 v0, s0, v50
	v_lshlrev_b32_e32 v0, 11, v0
	s_waitcnt lgkmcnt(0)
	v_cvt_pk_bf16_f32 v2, v34, v35
	ds_read2_b32 v[4:5], v47 offset0:90 offset1:123
	s_waitcnt lgkmcnt(0)
	v_cvt_pk_bf16_f32 v3, v4, v5
	ds_read2_b32 v[4:5], v47 offset0:156 offset1:189
	s_waitcnt lgkmcnt(0)
	v_cvt_pk_bf16_f32 v4, v4, v5
	ds_read2_b32 v[34:35], v47 offset0:222 offset1:255
	s_waitcnt lgkmcnt(0)
	v_cvt_pk_bf16_f32 v5, v34, v35
	v_lshl_add_u64 v[34:35], v[36:37], 0, v[0:1]
	global_store_dwordx4 v[34:35], v[2:5], off nt
	s_waitcnt lgkmcnt(0)

; __device__ __forceinline__ unsigned cvt_pk_bf16(float lo, float hi) { unsigned r; asm volatile("v_cvt_pk_bf16_f32 %0, %1, %2" : "=v"(r) : "v"(lo), "v"(hi)); return r; }
; template <int MAP>
; __device__ __forceinline__ void transpose_item(const float* __restrict__ W, int K, int N, bf16_t* __restrict__ WT, float* scr, int item, int lane) {
;     ...
; #pragma unroll 8
;     for (int i = 0; i < 32; ++i) { const int kk = 2 * i + (lane >> 5); scr[kk * 33 + (lane & 31)] = __builtin_nontemporal_load(W + (size_t)(k0 + kk) * N + n0 + (lane & 31)); }
;     asm volatile("s_waitcnt lgkmcnt(0)" ::: "memory");
;     const int c = lane & 7;
; #pragma unroll
;     for (int j = 0; j < 4; ++j) { const int n = (lane >> 3) + 8 * j; const float* s = scr + (8 * c) * 33 + n;
;         u32x4 o; o.x = cvt_pk_bf16(s[0 * 33], s[1 * 33]); o.y = cvt_pk_bf16(s[2 * 33], s[3 * 33]); o.z = cvt_pk_bf16(s[4 * 33], s[5 * 33]); o.w = cvt_pk_bf16(s[6 * 33], s[7 * 33]);
;         if (MAP == 1) *(u32x4*)(WT + (size_t)row_map<MAP>(n0 + n) * K + k0 + 8 * c) = o;
;         else __builtin_nontemporal_store(o, (u32x4*)(WT + (size_t)row_map<MAP>(n0 + n) * K + k0 + 8 * c)); }
.LBB0_260:
	v_lshl_add_u64 v[70:71], v[44:45], 0, s[0:1]
	v_lshl_add_u64 v[72:73], v[42:43], 0, s[0:1]
	v_lshl_add_u64 v[74:75], v[40:41], 0, s[0:1]
	v_lshl_add_u64 v[76:77], v[38:39], 0, s[0:1]
	v_lshl_add_u64 v[78:79], v[36:37], 0, s[0:1]
	v_lshl_add_u64 v[80:81], v[34:35], 0, s[0:1]
	v_lshl_add_u64 v[82:83], v[4:5], 0, s[0:1]
	v_lshl_add_u64 v[84:85], v[2:3], 0, s[0:1]
	global_load_dword v69, v[70:71], off nt
	s_nop 0
	global_load_dword v70, v[72:73], off nt
	global_load_dword v71, v[74:75], off nt
	s_nop 0
	global_load_dword v72, v[76:77], off nt
	global_load_dword v73, v[78:79], off nt
	global_load_dword v74, v[80:81], off nt
	global_load_dword v75, v[82:83], off nt
	s_nop 0
	global_load_dword v76, v[84:85], off nt
	s_add_u32 s0, s0, 0x20000
	s_addc_u32 s1, s1, 0
	v_add_u32_e32 v77, 0x400, v0
	s_cmp_lg_u32 s0, 0x80000
	v_lshl_add_u64 v[130:131], v[44:45], 0, s[0:1]
	v_lshl_add_u64 v[132:133], v[42:43], 0, s[0:1]
	v_lshl_add_u64 v[134:135], v[40:41], 0, s[0:1]
	v_lshl_add_u64 v[136:137], v[38:39], 0, s[0:1]
	v_lshl_add_u64 v[138:139], v[36:37], 0, s[0:1]
	v_lshl_add_u64 v[140:141], v[34:35], 0, s[0:1]
	v_lshl_add_u64 v[142:143], v[4:5], 0, s[0:1]
	v_lshl_add_u64 v[144:145], v[2:3], 0, s[0:1]
	global_load_dword v129, v[130:131], off nt
	s_nop 0
	global_load_dword v130, v[132:133], off nt
	global_load_dword v131, v[134:135], off nt
	s_nop 0
	global_load_dword v132, v[136:137], off nt
	global_load_dword v133, v[138:139], off nt
	global_load_dword v134, v[140:141], off nt
	global_load_dword v135, v[142:143], off nt
	s_nop 0
	global_load_dword v136, v[144:145], off nt
	s_add_u32 s0, s0, 0x20000
	s_addc_u32 s1, s1, 0
	v_add_u32_e32 v137, 0xc40, v0
	s_cmp_lg_u32 s0, 0x80000
	s_waitcnt vmcnt(14)
	ds_write2_b32 v0, v69, v70 offset1:66
	s_waitcnt vmcnt(12)
	ds_write2_b32 v0, v71, v72 offset0:132 offset1:198
	s_waitcnt vmcnt(10)
	ds_write2_b32 v77, v73, v74 offset0:8 offset1:74
	s_waitcnt vmcnt(8)
	ds_write2_b32 v77, v75, v76 offset0:140 offset1:206
	v_add_u32_e32 v0, 0x840, v0
	s_waitcnt vmcnt(6)
	ds_write2_b32 v0, v129, v130 offset1:66
	s_waitcnt vmcnt(4)
	ds_write2_b32 v0, v131, v132 offset0:132 offset1:198
	s_waitcnt vmcnt(2)
	ds_write2_b32 v137, v133, v134 offset0:8 offset1:74
	s_waitcnt vmcnt(0)
	ds_write2_b32 v137, v135, v136 offset0:140 offset1:206
	v_add_u32_e32 v0, 0x840, v0
	s_cbranch_scc1 .LBB0_260
	s_add_i32 s0, s18, 0xffffde00
	s_waitcnt lgkmcnt(0)
	s_and_b32 s1, s0, 0x1fc0
	s_lshl_b32 s0, s0, 5
	ds_read2_b32 v[2:3], v47 offset1:33
	s_and_b32 s0, s0, 0x7e0
	s_waitcnt lgkmcnt(0)
	v_cvt_pk_bf16_f32 v2, v2, v3
	ds_read2_b32 v[4:5], v47 offset0:66 offset1:99
	s_lshl_b32 s60, s1, 1
	v_or_b32_e32 v0, s0, v46
	s_waitcnt lgkmcnt(0)
	v_cvt_pk_bf16_f32 v3, v4, v5
	ds_read2_b32 v[4:5], v47 offset0:132 offset1:165
	v_lshl_add_u64 v[36:37], v[16:17], 0, s[60:61]
	v_lshlrev_b32_e32 v0, 11, v0
	s_waitcnt lgkmcnt(0)
	v_cvt_pk_bf16_f32 v4, v4, v5
	ds_read2_b32 v[34:35], v47 offset0:198 offset1:231
	s_waitcnt lgkmcnt(0)
	v_cvt_pk_bf16_f32 v5, v34, v35
	v_lshl_add_u64 v[38:39], v[36:37], 0, v[0:1]
	ds_read2_b32 v[34:35], v47 offset0:8 offset1:41
	global_store_dwordx4 v[38:39], v[2:5], off nt
	v_or_b32_e32 v0, s0, v48
	v_lshlrev_b32_e32 v0, 11, v0
	s_waitcnt lgkmcnt(0)
	v_cvt_pk_bf16_f32 v2, v34, v35
	ds_read2_b32 v[4:5], v47 offset0:74 offset1:107
	s_waitcnt lgkmcnt(0)
	v_cvt_pk_bf16_f32 v3, v4, v5
	ds_read2_b32 v[4:5], v47 offset0:140 offset1:173
	s_waitcnt lgkmcnt(0)
	v_cvt_pk_bf16_f32 v4, v4, v5
	ds_read2_b32 v[34:35], v47 offset0:206 offset1:239
	s_waitcnt lgkmcnt(0)
	v_cvt_pk_bf16_f32 v5, v34, v35
	v_lshl_add_u64 v[38:39], v[36:37], 0, v[0:1]
	ds_read2_b32 v[34:35], v47 offset0:16 offset1:49
	global_store_dwordx4 v[38:39], v[2:5], off nt
	v_or_b32_e32 v0, s0, v49
	v_lshlrev_b32_e32 v0, 11, v0
	s_waitcnt lgkmcnt(0)
	v_cvt_pk_bf16_f32 v2, v34, v35
	ds_read2_b32 v[4:5], v47 offset0:82 offset1:115
	s_waitcnt lgkmcnt(0)
	v_cvt_pk_bf16_f32 v3, v4, v5
	ds_read2_b32 v[4:5], v47 offset0:148 offset1:181
	s_waitcnt lgkmcnt(0)
	v_cvt_pk_bf16_f32 v4, v4, v5
	ds_read2_b32 v[34:35], v47 offset0:214 offset1:247
	s_waitcnt lgkmcnt(0)
	v_cvt_pk_bf16_f32 v5, v34, v35
	v_lshl_add_u64 v[38:39], v[36:37], 0, v[0:1]
	ds_read2_b32 v[34:35], v47 offset0:24 offset1:57
	global_store_dwordx4 v[38:39], v[2:5], off nt
	v_or_b32_e32 v0, s0, v50
	v_lshlrev_b32_e32 v0, 11, v0
	s_waitcnt lgkmcnt(0)
	v_cvt_pk_bf16_f32 v2, v34, v35
	ds_read2_b32 v[4:5], v47 offset0:90 offset1:123
	s_waitcnt lgkmcnt(0)
	v_cvt_pk_bf16_f32 v3, v4, v5
	ds_read2_b32 v[4:5], v47 offset0:156 offset1:189
	s_waitcnt lgkmcnt(0)
	v_cvt_pk_bf16_f32 v4, v4, v5
	ds_read2_b32 v[34:35], v47 offset0:222 offset1:255
	s_waitcnt lgkmcnt(0)
	v_cvt_pk_bf16_f32 v5, v34, v35
	v_lshl_add_u64 v[34:35], v[36:37], 0, v[0:1]
	global_store_dwordx4 v[34:35], v[2:5], off nt
	s_waitcnt lgkmcnt(0)

; __device__ __forceinline__ unsigned cvt_pk_bf16(float lo, float hi) { unsigned r; asm volatile("v_cvt_pk_bf16_f32 %0, %1, %2" : "=v"(r) : "v"(lo), "v"(hi)); return r; }
; template <int MAP>
; __device__ __forceinline__ int row_map(int n) {
;     if (MAP == 1) {
;         if (n < 1024) return (n & ~127) + ropeperm(n & 127);
;         if (n < 1280) return (n & ~127) + ropeperm(n & 127);
;         if (n < 1536) return 7424 + (n - 1280);
;         if (n < 2560) return 1280 + (n - 1536);
;         if (n < 3584) return 2304 + (n - 2560);
;         if (n < 4608) return 7680 + (n - 3584);
;         if (n < 6656) return 3328 + (n - 4608);
;         return 5376 + (n - 6656);
;     }
; template <int MAP>
; __device__ __forceinline__ void transpose_item(const float* __restrict__ W, int K, int N, bf16_t* __restrict__ WT, float* scr, int item, int lane) {
;     ...
; #pragma unroll 8
;     for (int i = 0; i < 32; ++i) { const int kk = 2 * i + (lane >> 5); scr[kk * 33 + (lane & 31)] = __builtin_nontemporal_load(W + (size_t)(k0 + kk) * N + n0 + (lane & 31)); }
;     asm volatile("s_waitcnt lgkmcnt(0)" ::: "memory");
;     const int c = lane & 7;
; #pragma unroll
;     for (int j = 0; j < 4; ++j) { const int n = (lane >> 3) + 8 * j; const float* s = scr + (8 * c) * 33 + n;
;         u32x4 o; o.x = cvt_pk_bf16(s[0 * 33], s[1 * 33]); o.y = cvt_pk_bf16(s[2 * 33], s[3 * 33]); o.z = cvt_pk_bf16(s[4 * 33], s[5 * 33]); o.w = cvt_pk_bf16(s[6 * 33], s[7 * 33]);
;         if (MAP == 1) *(u32x4*)(WT + (size_t)row_map<MAP>(n0 + n) * K + k0 + 8 * c) = o;
.LBB0_265:
	v_lshl_add_u64 v[70:71], v[44:45], 0, s[14:15]
	v_lshl_add_u64 v[72:73], v[42:43], 0, s[14:15]
	v_lshl_add_u64 v[74:75], v[40:41], 0, s[14:15]
	v_lshl_add_u64 v[76:77], v[38:39], 0, s[14:15]
	v_lshl_add_u64 v[78:79], v[36:37], 0, s[14:15]
	v_lshl_add_u64 v[80:81], v[34:35], 0, s[14:15]
	v_lshl_add_u64 v[82:83], v[4:5], 0, s[14:15]
	v_lshl_add_u64 v[84:85], v[2:3], 0, s[14:15]
	global_load_dword v69, v[70:71], off nt
	s_nop 0
	global_load_dword v70, v[72:73], off nt
	global_load_dword v71, v[74:75], off nt
	s_nop 0
	global_load_dword v72, v[76:77], off nt
	global_load_dword v73, v[78:79], off nt
	global_load_dword v74, v[80:81], off nt
	global_load_dword v75, v[82:83], off nt
	s_nop 0
	global_load_dword v76, v[84:85], off nt
	s_add_u32 s14, s14, 0x88000
	s_addc_u32 s15, s15, 0
	v_add_u32_e32 v77, 0x400, v0
	s_cmp_eq_u32 s14, 0x220000
	v_lshl_add_u64 v[130:131], v[44:45], 0, s[14:15]
	v_lshl_add_u64 v[132:133], v[42:43], 0, s[14:15]
	v_lshl_add_u64 v[134:135], v[40:41], 0, s[14:15]
	v_lshl_add_u64 v[136:137], v[38:39], 0, s[14:15]
	v_lshl_add_u64 v[138:139], v[36:37], 0, s[14:15]
	v_lshl_add_u64 v[140:141], v[34:35], 0, s[14:15]
	v_lshl_add_u64 v[142:143], v[4:5], 0, s[14:15]
	v_lshl_add_u64 v[144:145], v[2:3], 0, s[14:15]
	global_load_dword v129, v[130:131], off nt
	s_nop 0
	global_load_dword v130, v[132:133], off nt
	global_load_dword v131, v[134:135], off nt
	s_nop 0
	global_load_dword v132, v[136:137], off nt
	global_load_dword v133, v[138:139], off nt
	global_load_dword v134, v[140:141], off nt
	global_load_dword v135, v[142:143], off nt
	s_nop 0
	global_load_dword v136, v[144:145], off nt
	s_add_u32 s14, s14, 0x88000
	s_addc_u32 s15, s15, 0
	v_add_u32_e32 v137, 0xc40, v0
	s_cmp_eq_u32 s14, 0x220000
	s_waitcnt vmcnt(14)
	ds_write2_b32 v0, v69, v70 offset1:66
	s_waitcnt vmcnt(12)
	ds_write2_b32 v0, v71, v72 offset0:132 offset1:198
	s_waitcnt vmcnt(10)
	ds_write2_b32 v77, v73, v74 offset0:8 offset1:74
	s_waitcnt vmcnt(8)
	ds_write2_b32 v77, v75, v76 offset0:140 offset1:206
	v_add_u32_e32 v0, 0x840, v0
	s_waitcnt vmcnt(6)
	ds_write2_b32 v0, v129, v130 offset1:66
	s_waitcnt vmcnt(4)
	ds_write2_b32 v0, v131, v132 offset0:132 offset1:198
	s_waitcnt vmcnt(2)
	ds_write2_b32 v137, v133, v134 offset0:8 offset1:74
	s_waitcnt vmcnt(0)
	ds_write2_b32 v137, v135, v136 offset0:140 offset1:206
	v_add_u32_e32 v0, 0x840, v0
	s_cbranch_scc0 .LBB0_265
	s_waitcnt lgkmcnt(0)
	ds_read2_b32 v[2:3], v47 offset1:33
	s_waitcnt lgkmcnt(0)
	v_cvt_pk_bf16_f32 v2, v2, v3
	ds_read2_b32 v[4:5], v47 offset0:66 offset1:99
	v_or_b32_e32 v0, s0, v46
	s_movk_i32 s1, 0x3ff
	s_waitcnt lgkmcnt(0)
	v_cvt_pk_bf16_f32 v3, v4, v5
	ds_read2_b32 v[4:5], v47 offset0:132 offset1:165
	s_and_b32 s19, s0, 0x780
	v_cmp_lt_i32_e32 vcc, s1, v0
	s_waitcnt lgkmcnt(0)
	v_cvt_pk_bf16_f32 v4, v4, v5
	ds_read2_b32 v[34:35], v47 offset0:198 offset1:231
	s_waitcnt lgkmcnt(0)
	v_cvt_pk_bf16_f32 v5, v34, v35
	s_and_saveexec_b64 s[14:15], vcc
	s_xor_b64 s[14:15], exec, s[14:15]
	s_cbranch_execz .LBB0_288
	s_cmpk_gt_u32 s0, 0x4ff
	s_mov_b64 s[16:17], -1
	s_cbranch_scc0 .LBB0_285
	s_cmpk_gt_u32 s0, 0x5ff
	s_cbranch_scc0 .LBB0_282
	s_cmpk_gt_u32 s0, 0x9ff
	s_cbranch_scc0 .LBB0_279
	s_cmpk_gt_u32 s0, 0xdff
	s_cbranch_scc0 .LBB0_276
	s_cmpk_gt_u32 s0, 0x11ff
	s_cbranch_scc0 .LBB0_273
	v_add_u32_e32 v36, 0xfffffb00, v0
	s_mov_b64 s[16:17], 0
